# v062 + E1/H0/H1 fused epilogues: address arithmetic and the 20 first-pass loads issued ahead of the K-loop drain (vmcnt(20)) and its two barriers
# speedup vs baseline: 1.0042x; 1.0020x over previous
; #define PG8_WAIT_V(n) asm volatile("s_waitcnt vmcnt(" #n ")" ::: "memory")
; #define PG8_BAR __builtin_amdgcn_s_barrier()
; __device__ __forceinline__ float bf_lo(unsigned w) { return __uint_as_float(w << 16); }
; __device__ __forceinline__ float bf_hi(unsigned w) { return __uint_as_float(w & 0xffff0000u); }
; template <class Epi, class Sched, bool ALIGN_EPI = false, bool SP2 = false, bool PAIR_ACC = false>
; __device__ __forceinline__ void gemm_phase(PG8_LAS unsigned char* lds, const Gemm g, const Sched& S, const Epi& E) {
;     ...
;     PG8_WAIT_V(0);
;     if constexpr (!ALIGN_EPI) { if (wr == 0) PG8_BAR; }
;     PG8_BAR;
;     __device__ __forceinline__ void fused(f32x4 (&acc)[2][2][4][2], const Unit& u, int wr, int wc, int fr, int fq, PG8_LAS unsigned char* lds, int wid, int lane) const {
;     ...
;         const int col0 = u.pn * BM + wc * 32 + 8 * fq, b = u.pm >> 4;
;         {
;             f32x4 gv[2][2];
; #pragma unroll
;             for (int bj = 0; bj < 2; ++bj)
; #pragma unroll
;                 for (int n = 0; n < 2; ++n) gv[bj][n] = *(const f32x4*)(g + (size_t)b * 6144 + col0 + bj * HALF + 4 * n);
; #pragma unroll
;             for (int ai = 0; ai < 2; ++ai)
; #pragma unroll
;                 for (int m = 0; m < 4; ++m) { const int r = ai * HALF + wr * 64 + m * 16 + fr; const size_t off = (size_t)(u.pm * BM + r) * 1024 + col0;
; #pragma unroll
;                     for (int bj = 0; bj < 2; ++bj) { f32x4 b0, b1;
;                         if (XIN_BF16) { const u32x4 w = *(const u32x4*)((const bf16_t*)xin + off + bj * HALF); b0 = (f32x4){bf_lo(w.x), bf_hi(w.x), bf_lo(w.y), bf_hi(w.y)}; b1 = (f32x4){bf_lo(w.z), bf_hi(w.z), bf_lo(w.w), bf_hi(w.w)}; }
;                         else { b0 = *(const f32x4*)((const float*)xin + off + bj * HALF); b1 = *(const f32x4*)((const float*)xin + off + bj * HALF + 4); }
;                         acc[ai][bj][m][0] = b0 + gv[bj][0] * acc[ai][bj][m][0]; acc[ai][bj][m][1] = b1 + gv[bj][1] * acc[ai][bj][m][1]; }
.LBB0_940:
	s_add_u32 s6, s12, 0xc800000
	s_addc_u32 s7, s13, 0
	s_lshl_b32 s8, s25, 5
	s_lshl_b32 s9, s18, 8
	v_lshrrev_b32_e32 v130, 1, v168
	s_or_b32 s8, s9, s8
	v_and_or_b32 v156, v130, 24, s8
	s_ashr_i32 s8, s5, 4
	s_mul_i32 s35, s8, 0x6000
	s_mul_hi_i32 s34, s8, 0x6000
	s_add_u32 s8, s12, s35
	s_addc_u32 s9, s13, s34
	s_lshl_b32 s30, s5, 8
	v_add_u32_e32 v164, s30, v166
	v_ashrrev_i32_e32 v165, 31, v164
	v_ashrrev_i32_e32 v157, 31, v156
	v_lshlrev_b64 v[150:151], 11, v[164:165]
	v_lshl_add_u64 v[130:131], s[6:7], 0, v[150:151]
	v_lshlrev_b64 v[146:147], 1, v[156:157]
	v_lshl_add_u64 v[130:131], v[130:131], 0, v[146:147]
	v_lshl_add_u64 v[132:133], v[156:157], 2, s[8:9]
	s_movk_i32 s10, 0x5000
	s_mov_b64 s[98:99], 0x8000
	v_lshl_add_u64 v[198:199], v[130:131], 0, s[98:99]
	global_load_dwordx4 v[206:209], v[198:199], off nt
	global_load_dwordx4 v[210:213], v[198:199], off offset:256 nt
	s_mov_b64 s[98:99], 0x10000
	v_lshl_add_u64 v[198:199], v[130:131], 0, s[98:99]
	global_load_dwordx4 v[214:217], v[198:199], off nt
	global_load_dwordx4 v[218:221], v[198:199], off offset:256 nt
	s_mov_b64 s[98:99], 0x18000
	v_lshl_add_u64 v[198:199], v[130:131], 0, s[98:99]
	global_load_dwordx4 v[222:225], v[198:199], off nt
	global_load_dwordx4 v[226:229], v[198:199], off offset:256 nt
	s_mov_b64 s[98:99], 0x40000
	v_lshl_add_u64 v[198:199], v[130:131], 0, s[98:99]
	global_load_dwordx4 v[230:233], v[198:199], off nt
	global_load_dwordx4 v[234:237], v[198:199], off offset:256 nt
	s_mov_b64 s[98:99], 0x48000
	v_lshl_add_u64 v[198:199], v[130:131], 0, s[98:99]
	global_load_dwordx4 v[238:241], v[198:199], off nt
	global_load_dwordx4 v[242:245], v[198:199], off offset:256 nt
	s_mov_b64 s[98:99], 0x50000
	v_lshl_add_u64 v[198:199], v[130:131], 0, s[98:99]
	global_load_dwordx4 v[248:251], v[198:199], off nt
	global_load_dwordx4 v[252:255], v[198:199], off offset:256 nt
	global_load_dwordx4 v[152:155], v[130:131], off nt
	global_load_dwordx4 v[158:161], v[130:131], off offset:256 nt
	v_add_co_u32_e32 v130, vcc, s10, v132
	s_mov_b64 s[8:9], 0x5000
	s_nop 0
	v_addc_co_u32_e32 v131, vcc, 0, v133, vcc
	global_load_dwordx4 v[138:141], v[130:131], off nt
	v_lshl_add_u64 v[130:131], v[132:133], 0, s[8:9]
	global_load_dwordx4 v[142:145], v[130:131], off offset:16 nt
	global_load_dwordx4 v[134:137], v[130:131], off offset:512 nt
	s_nop 0
	global_load_dwordx4 v[130:133], v[130:131], off offset:528 nt
	v_add_u32_e32 v148, 16, v164
	v_ashrrev_i32_e32 v149, 31, v148
	v_lshlrev_b64 v[148:149], 11, v[148:149]
	v_lshl_add_u64 v[162:163], s[6:7], 0, v[148:149]
	v_lshl_add_u64 v[162:163], v[162:163], 0, v[146:147]
	v_mbcnt_hi_u32_b32 v173, -1, v1
	v_and_b32_e32 v169, 64, v173
	v_xor_b32_e32 v165, 16, v173
	v_add_u32_e32 v194, 64, v169
	v_cmp_lt_i32_e32 vcc, v165, v194
	s_waitcnt vmcnt(0)
	v_lshlrev_b32_e32 v170, 16, v152
	v_and_b32_e32 v171, 0xffff0000, v152
	v_lshlrev_b32_e32 v152, 16, v153
	v_and_b32_e32 v153, 0xffff0000, v153
	v_lshlrev_b32_e32 v174, 16, v154
	v_and_b32_e32 v175, 0xffff0000, v154
	v_lshlrev_b32_e32 v154, 16, v155
	v_and_b32_e32 v155, 0xffff0000, v155
	v_lshlrev_b32_e32 v176, 16, v158
	v_and_b32_e32 v177, 0xffff0000, v158
	v_lshlrev_b32_e32 v158, 16, v159
	v_and_b32_e32 v159, 0xffff0000, v159
	v_lshlrev_b32_e32 v178, 16, v160
	v_and_b32_e32 v179, 0xffff0000, v160
	v_lshlrev_b32_e32 v160, 16, v161
	v_and_b32_e32 v161, 0xffff0000, v161
	v_pk_fma_f32 v[58:59], v[58:59], v[138:139], v[170:171]
	v_pk_fma_f32 v[60:61], v[60:61], v[140:141], v[152:153]
	v_pk_fma_f32 v[64:65], v[64:65], v[144:145], v[154:155]
	v_pk_fma_f32 v[62:63], v[62:63], v[142:143], v[174:175]
	v_pk_fma_f32 v[56:57], v[56:57], v[136:137], v[158:159]
	v_pk_fma_f32 v[54:55], v[54:55], v[134:135], v[176:177]
	v_pk_fma_f32 v[48:49], v[48:49], v[132:133], v[160:161]
	v_pk_fma_f32 v[46:47], v[46:47], v[130:131], v[178:179]
	v_add_u32_e32 v152, 32, v164
	v_mov_b32_e32 v158, v206
	v_mov_b32_e32 v159, v207
	v_mov_b32_e32 v160, v208
	v_mov_b32_e32 v161, v209
	v_mov_b32_e32 v174, v210
	v_mov_b32_e32 v175, v211
	v_mov_b32_e32 v176, v212
	v_mov_b32_e32 v177, v213
	v_ashrrev_i32_e32 v153, 31, v152
	v_lshlrev_b64 v[152:153], 11, v[152:153]
	v_lshl_add_u64 v[154:155], s[6:7], 0, v[152:153]
	v_lshl_add_u64 v[154:155], v[154:155], 0, v[146:147]
	v_cndmask_b32_e32 v165, v173, v165, vcc
	v_lshlrev_b32_e32 v169, 2, v165
	s_waitcnt vmcnt(1)
	v_lshlrev_b32_e32 v162, 16, v158
	v_and_b32_e32 v163, 0xffff0000, v158
	v_lshlrev_b32_e32 v158, 16, v159
	v_and_b32_e32 v159, 0xffff0000, v159
	v_lshlrev_b32_e32 v170, 16, v160
	v_and_b32_e32 v171, 0xffff0000, v160
	v_lshlrev_b32_e32 v160, 16, v161
	v_and_b32_e32 v161, 0xffff0000, v161
	s_waitcnt vmcnt(0)
	v_lshlrev_b32_e32 v178, 16, v174
	v_and_b32_e32 v179, 0xffff0000, v174
	v_lshlrev_b32_e32 v174, 16, v175
	v_and_b32_e32 v175, 0xffff0000, v175
	v_lshlrev_b32_e32 v180, 16, v176
	v_and_b32_e32 v181, 0xffff0000, v176
	v_lshlrev_b32_e32 v176, 16, v177
	v_and_b32_e32 v177, 0xffff0000, v177
	v_pk_fma_f32 v[84:85], v[84:85], v[140:141], v[158:159]
	v_pk_fma_f32 v[82:83], v[82:83], v[138:139], v[162:163]
	v_pk_fma_f32 v[76:77], v[76:77], v[144:145], v[160:161]
	v_pk_fma_f32 v[74:75], v[74:75], v[142:143], v[170:171]
	v_pk_fma_f32 v[52:53], v[52:53], v[136:137], v[174:175]
	v_pk_fma_f32 v[50:51], v[50:51], v[134:135], v[178:179]
	v_pk_fma_f32 v[44:45], v[44:45], v[132:133], v[176:177]
	v_pk_fma_f32 v[42:43], v[42:43], v[130:131], v[180:181]
	s_nop 0
	v_mov_b32_e32 v158, v214
	v_mov_b32_e32 v159, v215
	v_mov_b32_e32 v160, v216
	v_mov_b32_e32 v161, v217
	v_mov_b32_e32 v174, v218
	v_mov_b32_e32 v175, v219
	v_mov_b32_e32 v176, v220
	v_mov_b32_e32 v177, v221
	v_add_u32_e32 v154, 48, v164
	v_ashrrev_i32_e32 v155, 31, v154
	v_lshlrev_b64 v[154:155], 11, v[154:155]
	v_lshl_add_u64 v[162:163], s[6:7], 0, v[154:155]
	v_lshl_add_u64 v[170:171], v[162:163], 0, v[146:147]
	s_waitcnt vmcnt(1)
; __device__ __forceinline__ float bf_lo(unsigned w) { return __uint_as_float(w << 16); }
; __device__ __forceinline__ float bf_hi(unsigned w) { return __uint_as_float(w & 0xffff0000u); }
;     __device__ __forceinline__ void fused(f32x4 (&acc)[2][2][4][2], const Unit& u, int wr, int wc, int fr, int fq, PG8_LAS unsigned char* lds, int wid, int lane) const {
;     ...
;             for (int ai = 0; ai < 2; ++ai)
; #pragma unroll
;                 for (int m = 0; m < 4; ++m) { const int r = ai * HALF + wr * 64 + m * 16 + fr; const size_t off = (size_t)(u.pm * BM + r) * 1024 + col0;
; #pragma unroll
;                     for (int bj = 0; bj < 2; ++bj) { f32x4 b0, b1;
;                         if (XIN_BF16) { const u32x4 w = *(const u32x4*)((const bf16_t*)xin + off + bj * HALF); b0 = (f32x4){bf_lo(w.x), bf_hi(w.x), bf_lo(w.y), bf_hi(w.y)}; b1 = (f32x4){bf_lo(w.z), bf_hi(w.z), bf_lo(w.w), bf_hi(w.w)}; }
;                         else { b0 = *(const f32x4*)((const float*)xin + off + bj * HALF); b1 = *(const f32x4*)((const float*)xin + off + bj * HALF + 4); }
;                         acc[ai][bj][m][0] = b0 + gv[bj][0] * acc[ai][bj][m][0]; acc[ai][bj][m][1] = b1 + gv[bj][1] * acc[ai][bj][m][1]; }
	v_lshlrev_b32_e32 v162, 16, v158
	v_and_b32_e32 v163, 0xffff0000, v158
	v_lshlrev_b32_e32 v158, 16, v159
	v_and_b32_e32 v159, 0xffff0000, v159
	v_lshlrev_b32_e32 v178, 16, v160
	v_and_b32_e32 v179, 0xffff0000, v160
	v_lshlrev_b32_e32 v160, 16, v161
	v_and_b32_e32 v161, 0xffff0000, v161
	s_waitcnt vmcnt(0)
	v_lshlrev_b32_e32 v180, 16, v174
	v_and_b32_e32 v181, 0xffff0000, v174
	v_lshlrev_b32_e32 v174, 16, v175
	v_and_b32_e32 v175, 0xffff0000, v175
	v_lshlrev_b32_e32 v182, 16, v176
	v_and_b32_e32 v183, 0xffff0000, v176
	v_lshlrev_b32_e32 v176, 16, v177
	v_and_b32_e32 v177, 0xffff0000, v177
	v_pk_fma_f32 v[100:101], v[100:101], v[140:141], v[158:159]
	v_pk_fma_f32 v[98:99], v[98:99], v[138:139], v[162:163]
	v_pk_fma_f32 v[92:93], v[92:93], v[144:145], v[160:161]
	v_pk_fma_f32 v[90:91], v[90:91], v[142:143], v[178:179]
	v_pk_fma_f32 v[80:81], v[80:81], v[136:137], v[174:175]
	v_pk_fma_f32 v[78:79], v[78:79], v[134:135], v[180:181]
	v_pk_fma_f32 v[72:73], v[72:73], v[132:133], v[176:177]
	v_pk_fma_f32 v[70:71], v[70:71], v[130:131], v[182:183]
	v_add_u32_e32 v158, 0x80, v164
	v_mov_b32_e32 v160, v222
	v_mov_b32_e32 v161, v223
	v_mov_b32_e32 v162, v224
	v_mov_b32_e32 v163, v225
	v_mov_b32_e32 v174, v226
	v_mov_b32_e32 v175, v227
	v_mov_b32_e32 v176, v228
	v_mov_b32_e32 v177, v229
	v_ashrrev_i32_e32 v159, 31, v158
	v_lshlrev_b64 v[158:159], 11, v[158:159]
	v_lshl_add_u64 v[170:171], s[6:7], 0, v[158:159]
	v_lshl_add_u64 v[170:171], v[170:171], 0, v[146:147]
	s_waitcnt vmcnt(1)
	v_lshlrev_b32_e32 v178, 16, v160
	v_and_b32_e32 v179, 0xffff0000, v160
	v_lshlrev_b32_e32 v160, 16, v161
	v_and_b32_e32 v161, 0xffff0000, v161
	v_lshlrev_b32_e32 v180, 16, v162
	v_and_b32_e32 v181, 0xffff0000, v162
	v_lshlrev_b32_e32 v162, 16, v163
	v_and_b32_e32 v163, 0xffff0000, v163
	s_waitcnt vmcnt(0)
	v_lshlrev_b32_e32 v182, 16, v174
	v_and_b32_e32 v183, 0xffff0000, v174
	v_lshlrev_b32_e32 v174, 16, v175
	v_and_b32_e32 v175, 0xffff0000, v175
	v_lshlrev_b32_e32 v184, 16, v176
	v_and_b32_e32 v185, 0xffff0000, v176
	v_lshlrev_b32_e32 v176, 16, v177
	v_and_b32_e32 v177, 0xffff0000, v177
	v_pk_fma_f32 v[116:117], v[116:117], v[140:141], v[160:161]
	v_pk_fma_f32 v[114:115], v[114:115], v[138:139], v[178:179]
	v_pk_fma_f32 v[112:113], v[112:113], v[144:145], v[162:163]
	v_pk_fma_f32 v[110:111], v[110:111], v[142:143], v[180:181]
	v_pk_fma_f32 v[104:105], v[104:105], v[136:137], v[174:175]
	v_pk_fma_f32 v[102:103], v[102:103], v[134:135], v[182:183]
	v_pk_fma_f32 v[96:97], v[96:97], v[132:133], v[176:177]
	v_pk_fma_f32 v[94:95], v[94:95], v[130:131], v[184:185]
	v_add_u32_e32 v160, 0x90, v164
	v_mov_b32_e32 v174, v230
	v_mov_b32_e32 v175, v231
	v_mov_b32_e32 v176, v232
	v_mov_b32_e32 v177, v233
	v_mov_b32_e32 v178, v234
	v_mov_b32_e32 v179, v235
	v_mov_b32_e32 v180, v236
	v_mov_b32_e32 v181, v237
	v_ashrrev_i32_e32 v161, 31, v160
	v_lshlrev_b64 v[160:161], 11, v[160:161]
	v_lshl_add_u64 v[162:163], s[6:7], 0, v[160:161]
	v_lshl_add_u64 v[162:163], v[162:163], 0, v[146:147]
	s_waitcnt vmcnt(1)
	v_lshlrev_b32_e32 v170, 16, v174
	v_and_b32_e32 v171, 0xffff0000, v174
	v_lshlrev_b32_e32 v174, 16, v175
	v_and_b32_e32 v175, 0xffff0000, v175
	v_lshlrev_b32_e32 v182, 16, v176
	v_and_b32_e32 v183, 0xffff0000, v176
	v_lshlrev_b32_e32 v176, 16, v177
	v_and_b32_e32 v177, 0xffff0000, v177
	s_waitcnt vmcnt(0)
	v_lshlrev_b32_e32 v184, 16, v178
	v_and_b32_e32 v185, 0xffff0000, v178
	v_lshlrev_b32_e32 v178, 16, v179
	v_and_b32_e32 v179, 0xffff0000, v179
	v_lshlrev_b32_e32 v186, 16, v180
	v_and_b32_e32 v187, 0xffff0000, v180
	v_lshlrev_b32_e32 v180, 16, v181
	v_and_b32_e32 v181, 0xffff0000, v181
	v_pk_fma_f32 v[128:129], v[128:129], v[140:141], v[174:175]
	v_pk_fma_f32 v[126:127], v[126:127], v[138:139], v[170:171]
	v_pk_fma_f32 v[124:125], v[124:125], v[144:145], v[176:177]
	v_pk_fma_f32 v[122:123], v[122:123], v[142:143], v[182:183]
	v_pk_fma_f32 v[120:121], v[120:121], v[136:137], v[178:179]
	v_pk_fma_f32 v[118:119], v[118:119], v[134:135], v[184:185]
	v_pk_fma_f32 v[108:109], v[108:109], v[132:133], v[180:181]
	v_pk_fma_f32 v[106:107], v[106:107], v[130:131], v[186:187]
	s_nop 0
	v_mov_b32_e32 v174, v238
	v_mov_b32_e32 v175, v239
	v_mov_b32_e32 v176, v240
	v_mov_b32_e32 v177, v241
	v_mov_b32_e32 v178, v242
	v_mov_b32_e32 v179, v243
	v_mov_b32_e32 v180, v244
	v_mov_b32_e32 v181, v245
	v_add_u32_e32 v162, 0xa0, v164
	v_ashrrev_i32_e32 v163, 31, v162
	v_lshlrev_b64 v[162:163], 11, v[162:163]
	v_lshl_add_u64 v[170:171], s[6:7], 0, v[162:163]
	v_lshl_add_u64 v[170:171], v[170:171], 0, v[146:147]
	v_add_u32_e32 v164, 0xb0, v164
	v_ashrrev_i32_e32 v165, 31, v164
	v_lshlrev_b64 v[164:165], 11, v[164:165]
	s_waitcnt vmcnt(1)
	v_lshlrev_b32_e32 v182, 16, v174
	v_and_b32_e32 v183, 0xffff0000, v174
	v_lshlrev_b32_e32 v174, 16, v175
	v_and_b32_e32 v175, 0xffff0000, v175
	v_lshlrev_b32_e32 v184, 16, v176
	v_and_b32_e32 v185, 0xffff0000, v176
	v_lshlrev_b32_e32 v176, 16, v177
	v_and_b32_e32 v177, 0xffff0000, v177
	s_waitcnt vmcnt(0)
	v_lshlrev_b32_e32 v186, 16, v178
	v_and_b32_e32 v187, 0xffff0000, v178
	v_lshlrev_b32_e32 v178, 16, v179
	v_and_b32_e32 v179, 0xffff0000, v179
	v_lshlrev_b32_e32 v188, 16, v180
	v_and_b32_e32 v189, 0xffff0000, v180
	v_lshlrev_b32_e32 v180, 16, v181
	v_and_b32_e32 v181, 0xffff0000, v181
	v_pk_fma_f32 v[88:89], v[88:89], v[140:141], v[174:175]
	v_pk_fma_f32 v[86:87], v[86:87], v[138:139], v[182:183]
	v_pk_fma_f32 v[68:69], v[68:69], v[144:145], v[176:177]
	v_pk_fma_f32 v[66:67], v[66:67], v[142:143], v[184:185]
	v_pk_fma_f32 v[40:41], v[40:41], v[136:137], v[178:179]
	v_pk_fma_f32 v[38:39], v[38:39], v[134:135], v[186:187]
	v_pk_fma_f32 v[36:37], v[36:37], v[132:133], v[180:181]
	v_pk_fma_f32 v[34:35], v[34:35], v[130:131], v[188:189]
	v_mov_b32_e32 v184, v59
	v_mov_b32_e32 v174, v248
	v_mov_b32_e32 v175, v249
	v_mov_b32_e32 v176, v250
	v_mov_b32_e32 v177, v251
	v_mov_b32_e32 v178, v252
	v_mov_b32_e32 v179, v253
	v_mov_b32_e32 v180, v254
	v_mov_b32_e32 v181, v255
	v_lshl_add_u64 v[170:171], s[6:7], 0, v[164:165]
	v_lshl_add_u64 v[170:171], v[170:171], 0, v[146:147]
	v_mov_b32_e32 v185, v60
	v_mov_b32_e32 v186, v58
	v_mov_b32_e32 v187, v61
	v_pk_add_f32 v[184:185], v[184:185], v[186:187]
	s_lshl_b32 s6, s25, 3
	s_add_i32 s8, s6, 0
	s_waitcnt vmcnt(1)
; #define PG8_WAIT_V(n) asm volatile("s_waitcnt vmcnt(" #n ")" ::: "memory")
; #define PG8_BAR __builtin_amdgcn_s_barrier()
; template <class Epi, class Sched, bool ALIGN_EPI = false, bool SP2 = false, bool PAIR_ACC = false>
; __device__ __forceinline__ void gemm_phase(PG8_LAS unsigned char* lds, const Gemm g, const Sched& S, const Epi& E) {
;     ...
;     PG8_WAIT_V(0);
;     if constexpr (!ALIGN_EPI) { if (wr == 0) PG8_BAR; }
;     PG8_BAR;
;     template <class Mid> __device__ __forceinline__ bool run(const f32x4 (&v)[2][2][4][2], const Unit& u, int wr, int wc, int fr, int fq, PG8_LAS unsigned char* lds, int wid, int lane, const Mid& mid) const {
;     ...
;         for (int ai = 0; ai < 2; ++ai)
; #pragma unroll
;             for (int m = 0; m < 4; ++m) {
;                 float s = 0.f;
; #pragma unroll
;                 for (int bj = 0; bj < 2; ++bj)
; #pragma unroll
;                     for (int n = 0; n < 2; ++n) { const f32x4 x = v[ai][bj][m][n]; s += (x[0] + x[1]) + (x[2] + x[3]); }
;                 s += __shfl_xor(s, 16); s += __shfl_xor(s, 32);
;                 const float mw = s * (1.0f / 64.0f); float q = 0.f;
; #pragma unroll
;                 for (int bj = 0; bj < 2; ++bj)
; #pragma unroll
;                     for (int n = 0; n < 2; ++n) { const f32x4 d = v[ai][bj][m][n] - mw; q += (d[0] * d[0] + d[1] * d[1]) + (d[2] * d[2] + d[3] * d[3]); }
;                 q += __shfl_xor(q, 16); q += __shfl_xor(q, 32);
;                 if (fq == 0) P[(ai * HALF + wr * 64 + m * 16 + fr) * 4 + wc] = (f32x2v){mw, q};
	v_lshlrev_b32_e32 v182, 16, v174
	v_and_b32_e32 v183, 0xffff0000, v174
	v_lshlrev_b32_e32 v174, 16, v175
	v_and_b32_e32 v175, 0xffff0000, v175
	v_lshlrev_b32_e32 v188, 16, v176
	v_and_b32_e32 v189, 0xffff0000, v176
	v_lshlrev_b32_e32 v176, 16, v177
	v_and_b32_e32 v177, 0xffff0000, v177
	s_waitcnt vmcnt(0)
	v_lshlrev_b32_e32 v190, 16, v178
	v_and_b32_e32 v191, 0xffff0000, v178
	v_lshlrev_b32_e32 v178, 16, v179
	v_and_b32_e32 v179, 0xffff0000, v179
	v_lshlrev_b32_e32 v192, 16, v180
	v_and_b32_e32 v193, 0xffff0000, v180
	v_lshlrev_b32_e32 v180, 16, v181
	v_and_b32_e32 v181, 0xffff0000, v181
	v_pk_fma_f32 v[32:33], v[32:33], v[140:141], v[174:175]
	v_pk_fma_f32 v[30:31], v[30:31], v[138:139], v[182:183]
	v_pk_fma_f32 v[28:29], v[28:29], v[144:145], v[176:177]
	v_pk_fma_f32 v[26:27], v[26:27], v[142:143], v[188:189]
	v_pk_fma_f32 v[24:25], v[24:25], v[136:137], v[178:179]
	v_pk_fma_f32 v[22:23], v[22:23], v[134:135], v[190:191]
	v_pk_fma_f32 v[20:21], v[20:21], v[132:133], v[180:181]
	v_pk_fma_f32 v[18:19], v[18:19], v[130:131], v[192:193]
	v_mov_b32_e32 v174, v63
	global_load_dwordx4 v[176:179], v[170:171], off nt
	global_load_dwordx4 v[180:183], v[170:171], off offset:256 nt
	s_waitcnt vmcnt(20)
	s_cmpk_gt_u32 s4, 0xff
	s_cbranch_scc1 .LBB0_942
	s_barrier
.LBB0_942:
	s_barrier
	v_mov_b32_e32 v175, v64
	v_mov_b32_e32 v188, v62
	v_mov_b32_e32 v189, v65
	v_pk_add_f32 v[174:175], v[174:175], v[188:189]
	v_add_f32_e32 v171, v184, v185
	v_pk_add_f32 v[174:175], v[174:175], v[174:175] op_sel_hi:[0,1]
	v_add_f32_e32 v191, v54, v55
	v_add_f32_e32 v193, v56, v57
	v_mov_b32_e32 v190, v46
	v_mov_b32_e32 v192, v47
	v_mov_b32_e32 v170, v49
	v_add_f32_e32 v171, 0, v171
	v_mov_b32_e32 v174, v48
	v_pk_add_f32 v[186:187], v[190:191], v[192:193]
	v_pk_add_f32 v[170:171], v[174:175], v[170:171]
	s_nop 0
	v_pk_add_f32 v[170:171], v[186:187], v[170:171]
	s_nop 0
	v_add_f32_e32 v170, v170, v171
	ds_bpermute_b32 v174, v169, v170
	v_xor_b32_e32 v171, 32, v173
	v_cmp_lt_i32_e32 vcc, v171, v194
	s_waitcnt lgkmcnt(0)
	v_add_f32_e32 v170, v170, v174
	v_cndmask_b32_e32 v171, v173, v171, vcc
	v_lshlrev_b32_e32 v171, 2, v171
	ds_bpermute_b32 v173, v171, v170
	s_waitcnt lgkmcnt(0)
	v_add_f32_e32 v173, v170, v173
	v_fmamk_f32 v174, v173, 0xbc800000, v61
	v_fmamk_f32 v184, v173, 0xbc800000, v59
	v_fmamk_f32 v186, v173, 0xbc800000, v65
	v_fmamk_f32 v188, v173, 0xbc800000, v63
	v_fmamk_f32 v170, v173, 0xbc800000, v60
	v_fmamk_f32 v175, v173, 0xbc800000, v58
	v_fmamk_f32 v185, v173, 0xbc800000, v64
	v_fmamk_f32 v187, v173, 0xbc800000, v62
	v_fmamk_f32 v190, v173, 0xbc800000, v57
	v_fmamk_f32 v192, v173, 0xbc800000, v55
	v_mul_f32_e32 v184, v184, v184
	v_mul_f32_e32 v174, v174, v174
	v_mul_f32_e32 v188, v188, v188
	v_mul_f32_e32 v186, v186, v186
	v_fmamk_f32 v189, v173, 0xbc800000, v56
	v_fmamk_f32 v191, v173, 0xbc800000, v54
	v_fmamk_f32 v194, v173, 0xbc800000, v49
	v_fmamk_f32 v196, v173, 0xbc800000, v47
	v_mul_f32_e32 v192, v192, v192
	v_mul_f32_e32 v190, v190, v190
	v_fmac_f32_e32 v184, v175, v175
	v_fmac_f32_e32 v174, v170, v170
	v_fmac_f32_e32 v188, v187, v187
	v_fmac_f32_e32 v186, v185, v185
	v_fmamk_f32 v193, v173, 0xbc800000, v48
	v_fmamk_f32 v195, v173, 0xbc800000, v46
	v_mul_f32_e32 v196, v196, v196
	v_mul_f32_e32 v194, v194, v194
	v_fmac_f32_e32 v192, v191, v191
	v_fmac_f32_e32 v190, v189, v189
	v_add_f32_e32 v170, v184, v174
	v_add_f32_e32 v174, v188, v186
	v_fmac_f32_e32 v196, v195, v195
	v_fmac_f32_e32 v194, v193, v193
	v_add_f32_e32 v175, v192, v190
	v_add_f32_e32 v170, v170, v174
	v_add_f32_e32 v184, v196, v194
	v_add_f32_e32 v170, v175, v170
	v_add_f32_e32 v174, v184, v170
	ds_bpermute_b32 v175, v169, v174
	v_and_b32_e32 v170, 63, v168
	v_cmp_gt_u32_e32 vcc, 16, v170
	s_waitcnt lgkmcnt(0)
	v_add_f32_e32 v174, v174, v175
	ds_bpermute_b32 v175, v171, v174
	s_waitcnt vmcnt(1)
	v_lshlrev_b32_e32 v184, 16, v176
	v_and_b32_e32 v185, 0xffff0000, v176
	v_lshlrev_b32_e32 v176, 16, v177
	v_and_b32_e32 v177, 0xffff0000, v177
	v_lshlrev_b32_e32 v186, 16, v178
	v_and_b32_e32 v187, 0xffff0000, v178
	v_lshlrev_b32_e32 v178, 16, v179
	v_and_b32_e32 v179, 0xffff0000, v179
	s_waitcnt vmcnt(0)
	v_lshlrev_b32_e32 v188, 16, v180
	v_and_b32_e32 v189, 0xffff0000, v180
	v_lshlrev_b32_e32 v180, 16, v181
	v_and_b32_e32 v181, 0xffff0000, v181
	v_lshlrev_b32_e32 v190, 16, v182
	v_and_b32_e32 v191, 0xffff0000, v182
	v_lshlrev_b32_e32 v182, 16, v183
	v_and_b32_e32 v183, 0xffff0000, v183
	v_pk_fma_f32 v[16:17], v[16:17], v[140:141], v[176:177]
	v_pk_fma_f32 v[14:15], v[14:15], v[138:139], v[184:185]
	v_pk_fma_f32 v[12:13], v[12:13], v[144:145], v[178:179]
	v_pk_fma_f32 v[10:11], v[10:11], v[142:143], v[186:187]
	v_pk_fma_f32 v[8:9], v[8:9], v[136:137], v[180:181]
	v_pk_fma_f32 v[6:7], v[6:7], v[134:135], v[188:189]
	v_pk_fma_f32 v[4:5], v[4:5], v[132:133], v[182:183]
	v_pk_fma_f32 v[2:3], v[2:3], v[130:131], v[190:191]
	s_nop 0
	s_and_saveexec_b64 s[6:7], vcc
	s_cbranch_execz .LBB0_944
	s_lshl_b32 s9, s24, 11
	s_add_i32 s9, s8, s9
	v_mul_f32_e32 v130, 0x3c800000, v173
	s_waitcnt lgkmcnt(0)
	v_add_f32_e32 v131, v174, v175
	v_lshl_add_u32 v132, v167, 5, s9
	ds_write_b64 v132, v[130:131]

; #define PG8_WAIT_V(n) asm volatile("s_waitcnt vmcnt(" #n ")" ::: "memory")
; #define PG8_BAR __builtin_amdgcn_s_barrier()
; __device__ __forceinline__ float bf_lo(unsigned w) { return __uint_as_float(w << 16); }
; __device__ __forceinline__ float bf_hi(unsigned w) { return __uint_as_float(w & 0xffff0000u); }
; template <class Epi, class Sched, bool ALIGN_EPI = false, bool SP2 = false, bool PAIR_ACC = false>
; __device__ __forceinline__ void gemm_phase(PG8_LAS unsigned char* lds, const Gemm g, const Sched& S, const Epi& E) {
;     ...
;     PG8_WAIT_V(0);
;     if constexpr (!ALIGN_EPI) { if (wr == 0) PG8_BAR; }
;     PG8_BAR;
;     __device__ __forceinline__ void fused(f32x4 (&acc)[2][2][4][2], const Unit& u, int wr, int wc, int fr, int fq, PG8_LAS unsigned char* lds, int wid, int lane) const {
;     ...
;         const int col0 = u.pn * BM + wc * 32 + 8 * fq, b = u.pm >> 4;
;         {
;             f32x4 gv[2][2];
; #pragma unroll
;             for (int bj = 0; bj < 2; ++bj)
; #pragma unroll
;                 for (int n = 0; n < 2; ++n) gv[bj][n] = *(const f32x4*)(g + (size_t)b * 6144 + col0 + bj * HALF + 4 * n);
; #pragma unroll
;             for (int ai = 0; ai < 2; ++ai)
; #pragma unroll
;                 for (int m = 0; m < 4; ++m) { const int r = ai * HALF + wr * 64 + m * 16 + fr; const size_t off = (size_t)(u.pm * BM + r) * 1024 + col0;
; #pragma unroll
;                     for (int bj = 0; bj < 2; ++bj) { f32x4 b0, b1;
;                         if (XIN_BF16) { const u32x4 w = *(const u32x4*)((const bf16_t*)xin + off + bj * HALF); b0 = (f32x4){bf_lo(w.x), bf_hi(w.x), bf_lo(w.y), bf_hi(w.y)}; b1 = (f32x4){bf_lo(w.z), bf_hi(w.z), bf_lo(w.w), bf_hi(w.w)}; }
;                         else { b0 = *(const f32x4*)((const float*)xin + off + bj * HALF); b1 = *(const f32x4*)((const float*)xin + off + bj * HALF + 4); }
;                         acc[ai][bj][m][0] = b0 + gv[bj][0] * acc[ai][bj][m][0]; acc[ai][bj][m][1] = b1 + gv[bj][1] * acc[ai][bj][m][1]; }
.LBB0_1633:
	s_lshl_b32 s6, s19, 5
	s_lshl_b32 s7, s10, 8
	v_lshrrev_b32_e32 v130, 1, v168
	s_or_b32 s6, s7, s6
	v_and_or_b32 v156, v130, 24, s6
	s_ashr_i32 s6, s18, 4
	s_mul_i32 s34, s6, 0x6000
	s_mul_hi_i32 s25, s6, 0x6000
	s_add_u32 s6, s14, s34
	s_addc_u32 s7, s15, s25
	s_lshl_b32 s28, s18, 8
	v_add_u32_e32 v164, s28, v166
	v_ashrrev_i32_e32 v165, 31, v164
	v_ashrrev_i32_e32 v157, 31, v156
	v_lshlrev_b64 v[150:151], 11, v[164:165]
	v_lshl_add_u64 v[130:131], s[12:13], 0, v[150:151]
	v_lshlrev_b64 v[146:147], 1, v[156:157]
	v_lshl_add_u64 v[130:131], v[130:131], 0, v[146:147]
	v_lshl_add_u64 v[132:133], v[156:157], 2, s[6:7]
	s_mov_b32 s8, 0x1a000
	s_mov_b64 s[98:99], 0x8000
	v_lshl_add_u64 v[244:245], v[130:131], 0, s[98:99]
	global_load_dwordx4 v[196:199], v[244:245], off nt
	global_load_dwordx4 v[200:203], v[244:245], off offset:256 nt
	s_mov_b64 s[98:99], 0x10000
	v_lshl_add_u64 v[244:245], v[130:131], 0, s[98:99]
	global_load_dwordx4 v[204:207], v[244:245], off nt
	global_load_dwordx4 v[208:211], v[244:245], off offset:256 nt
	s_mov_b64 s[98:99], 0x18000
	v_lshl_add_u64 v[244:245], v[130:131], 0, s[98:99]
	global_load_dwordx4 v[212:215], v[244:245], off nt
	global_load_dwordx4 v[216:219], v[244:245], off offset:256 nt
	s_mov_b64 s[98:99], 0x40000
	v_lshl_add_u64 v[244:245], v[130:131], 0, s[98:99]
	global_load_dwordx4 v[220:223], v[244:245], off nt
	global_load_dwordx4 v[224:227], v[244:245], off offset:256 nt
	s_mov_b64 s[98:99], 0x48000
	v_lshl_add_u64 v[244:245], v[130:131], 0, s[98:99]
	global_load_dwordx4 v[228:231], v[244:245], off nt
	global_load_dwordx4 v[232:235], v[244:245], off offset:256 nt
	s_mov_b64 s[98:99], 0x50000
	v_lshl_add_u64 v[244:245], v[130:131], 0, s[98:99]
	global_load_dwordx4 v[236:239], v[244:245], off nt
	global_load_dwordx4 v[240:243], v[244:245], off offset:256 nt
	s_mov_b64 s[98:99], 0x58000
	v_lshl_add_u64 v[244:245], v[130:131], 0, s[98:99]
	global_load_dwordx4 v[248:251], v[244:245], off nt
	global_load_dwordx4 v[252:255], v[244:245], off offset:256 nt
	global_load_dwordx4 v[152:155], v[130:131], off nt
	global_load_dwordx4 v[158:161], v[130:131], off offset:256 nt
	v_add_co_u32_e32 v130, vcc, s8, v132
	s_mov_b64 s[6:7], 0x1a000
	s_nop 0
	v_addc_co_u32_e32 v131, vcc, 0, v133, vcc
	global_load_dwordx4 v[138:141], v[130:131], off nt
	v_lshl_add_u64 v[130:131], v[132:133], 0, s[6:7]
	global_load_dwordx4 v[142:145], v[130:131], off offset:16 nt
	global_load_dwordx4 v[134:137], v[130:131], off offset:512 nt
	s_nop 0
	global_load_dwordx4 v[130:133], v[130:131], off offset:528 nt
	s_waitcnt vmcnt(20)
	s_cmpk_gt_u32 s4, 0xff
	s_cbranch_scc1 .LBB0_1635
	s_barrier
.LBB0_1635:
	s_barrier
	v_add_u32_e32 v148, 16, v164
	v_ashrrev_i32_e32 v149, 31, v148
	v_lshlrev_b64 v[148:149], 11, v[148:149]
	v_lshl_add_u64 v[162:163], s[12:13], 0, v[148:149]
	v_lshl_add_u64 v[162:163], v[162:163], 0, v[146:147]
	v_mbcnt_hi_u32_b32 v192, -1, v1
	v_and_b32_e32 v169, 64, v192
	v_xor_b32_e32 v165, 16, v192
	v_add_u32_e32 v193, 64, v169
	v_cmp_lt_i32_e32 vcc, v165, v193
	s_lshl_b32 s6, s19, 3
	s_add_i32 s8, s6, 0
	v_cndmask_b32_e32 v165, v192, v165, vcc
	v_lshlrev_b32_e32 v169, 2, v165
	s_waitcnt vmcnt(0)
	v_lshlrev_b32_e32 v170, 16, v152
	v_and_b32_e32 v171, 0xffff0000, v152
	v_lshlrev_b32_e32 v152, 16, v153
	v_and_b32_e32 v153, 0xffff0000, v153
	v_lshlrev_b32_e32 v172, 16, v154
	v_and_b32_e32 v173, 0xffff0000, v154
	v_lshlrev_b32_e32 v154, 16, v155
	v_and_b32_e32 v155, 0xffff0000, v155
	v_lshlrev_b32_e32 v174, 16, v158
	v_and_b32_e32 v175, 0xffff0000, v158
	v_lshlrev_b32_e32 v158, 16, v159
	v_and_b32_e32 v159, 0xffff0000, v159
	v_lshlrev_b32_e32 v176, 16, v160
	v_and_b32_e32 v177, 0xffff0000, v160
	v_lshlrev_b32_e32 v160, 16, v161
	v_and_b32_e32 v161, 0xffff0000, v161
	v_pk_fma_f32 v[58:59], v[58:59], v[138:139], v[170:171]
	v_pk_fma_f32 v[60:61], v[60:61], v[140:141], v[152:153]
	v_pk_fma_f32 v[64:65], v[64:65], v[144:145], v[154:155]
	v_pk_fma_f32 v[62:63], v[62:63], v[142:143], v[172:173]
	v_pk_fma_f32 v[56:57], v[56:57], v[136:137], v[158:159]
	v_pk_fma_f32 v[54:55], v[54:55], v[134:135], v[174:175]
	v_pk_fma_f32 v[48:49], v[48:49], v[132:133], v[160:161]
	v_pk_fma_f32 v[46:47], v[46:47], v[130:131], v[176:177]
	v_add_u32_e32 v152, 32, v164
	v_mov_b32_e32 v158, v196
	v_mov_b32_e32 v159, v197
	v_mov_b32_e32 v160, v198
	v_mov_b32_e32 v161, v199
	v_mov_b32_e32 v170, v200
	v_mov_b32_e32 v171, v201
	v_mov_b32_e32 v172, v202
	v_mov_b32_e32 v173, v203
	v_ashrrev_i32_e32 v153, 31, v152
	v_lshlrev_b64 v[152:153], 11, v[152:153]
	v_lshl_add_u64 v[154:155], s[12:13], 0, v[152:153]
	v_lshl_add_u64 v[154:155], v[154:155], 0, v[146:147]
	s_waitcnt vmcnt(1)
	v_lshlrev_b32_e32 v162, 16, v158
	v_and_b32_e32 v163, 0xffff0000, v158
	v_lshlrev_b32_e32 v158, 16, v159
	v_and_b32_e32 v159, 0xffff0000, v159
	v_lshlrev_b32_e32 v174, 16, v160
	v_and_b32_e32 v175, 0xffff0000, v160
	v_lshlrev_b32_e32 v160, 16, v161
	v_and_b32_e32 v161, 0xffff0000, v161
	s_waitcnt vmcnt(0)
	v_lshlrev_b32_e32 v176, 16, v170
	v_and_b32_e32 v177, 0xffff0000, v170
	v_lshlrev_b32_e32 v170, 16, v171
	v_and_b32_e32 v171, 0xffff0000, v171
	v_lshlrev_b32_e32 v178, 16, v172
	v_and_b32_e32 v179, 0xffff0000, v172
	v_lshlrev_b32_e32 v172, 16, v173
	v_and_b32_e32 v173, 0xffff0000, v173
	v_pk_fma_f32 v[80:81], v[80:81], v[140:141], v[158:159]
	v_pk_fma_f32 v[78:79], v[78:79], v[138:139], v[162:163]
	v_pk_fma_f32 v[72:73], v[72:73], v[144:145], v[160:161]
	v_pk_fma_f32 v[70:71], v[70:71], v[142:143], v[174:175]
	v_pk_fma_f32 v[52:53], v[52:53], v[136:137], v[170:171]
	v_pk_fma_f32 v[50:51], v[50:51], v[134:135], v[176:177]
	v_pk_fma_f32 v[44:45], v[44:45], v[132:133], v[172:173]
	v_pk_fma_f32 v[42:43], v[42:43], v[130:131], v[178:179]
	s_nop 0
	v_mov_b32_e32 v158, v204
	v_mov_b32_e32 v159, v205
	v_mov_b32_e32 v160, v206
	v_mov_b32_e32 v161, v207
	v_mov_b32_e32 v170, v208
	v_mov_b32_e32 v171, v209
	v_mov_b32_e32 v172, v210
	v_mov_b32_e32 v173, v211
	v_add_u32_e32 v154, 48, v164
	v_ashrrev_i32_e32 v155, 31, v154
	v_lshlrev_b64 v[154:155], 11, v[154:155]
	v_lshl_add_u64 v[162:163], s[12:13], 0, v[154:155]
	v_lshl_add_u64 v[174:175], v[162:163], 0, v[146:147]
	s_waitcnt vmcnt(1)
; __device__ __forceinline__ float bf_lo(unsigned w) { return __uint_as_float(w << 16); }
; __device__ __forceinline__ float bf_hi(unsigned w) { return __uint_as_float(w & 0xffff0000u); }
;     __device__ __forceinline__ void fused(f32x4 (&acc)[2][2][4][2], const Unit& u, int wr, int wc, int fr, int fq, PG8_LAS unsigned char* lds, int wid, int lane) const {
;     ...
;             for (int ai = 0; ai < 2; ++ai)
; #pragma unroll
;                 for (int m = 0; m < 4; ++m) { const int r = ai * HALF + wr * 64 + m * 16 + fr; const size_t off = (size_t)(u.pm * BM + r) * 1024 + col0;
; #pragma unroll
;                     for (int bj = 0; bj < 2; ++bj) { f32x4 b0, b1;
;                         if (XIN_BF16) { const u32x4 w = *(const u32x4*)((const bf16_t*)xin + off + bj * HALF); b0 = (f32x4){bf_lo(w.x), bf_hi(w.x), bf_lo(w.y), bf_hi(w.y)}; b1 = (f32x4){bf_lo(w.z), bf_hi(w.z), bf_lo(w.w), bf_hi(w.w)}; }
;                         else { b0 = *(const f32x4*)((const float*)xin + off + bj * HALF); b1 = *(const f32x4*)((const float*)xin + off + bj * HALF + 4); }
;                         acc[ai][bj][m][0] = b0 + gv[bj][0] * acc[ai][bj][m][0]; acc[ai][bj][m][1] = b1 + gv[bj][1] * acc[ai][bj][m][1]; }
	v_lshlrev_b32_e32 v162, 16, v158
	v_and_b32_e32 v163, 0xffff0000, v158
	v_lshlrev_b32_e32 v158, 16, v159
	v_and_b32_e32 v159, 0xffff0000, v159
	v_lshlrev_b32_e32 v176, 16, v160
	v_and_b32_e32 v177, 0xffff0000, v160
	v_lshlrev_b32_e32 v160, 16, v161
	v_and_b32_e32 v161, 0xffff0000, v161
	s_waitcnt vmcnt(0)
	v_lshlrev_b32_e32 v178, 16, v170
	v_and_b32_e32 v179, 0xffff0000, v170
	v_lshlrev_b32_e32 v170, 16, v171
	v_and_b32_e32 v171, 0xffff0000, v171
	v_lshlrev_b32_e32 v180, 16, v172
	v_and_b32_e32 v181, 0xffff0000, v172
	v_lshlrev_b32_e32 v172, 16, v173
	v_and_b32_e32 v173, 0xffff0000, v173
	v_pk_fma_f32 v[100:101], v[100:101], v[140:141], v[158:159]
	v_pk_fma_f32 v[98:99], v[98:99], v[138:139], v[162:163]
	v_pk_fma_f32 v[92:93], v[92:93], v[144:145], v[160:161]
	v_pk_fma_f32 v[90:91], v[90:91], v[142:143], v[176:177]
	v_pk_fma_f32 v[76:77], v[76:77], v[136:137], v[170:171]
	v_pk_fma_f32 v[74:75], v[74:75], v[134:135], v[178:179]
	v_pk_fma_f32 v[68:69], v[68:69], v[132:133], v[172:173]
	v_pk_fma_f32 v[66:67], v[66:67], v[130:131], v[180:181]
	v_add_u32_e32 v158, 0x80, v164
	v_mov_b32_e32 v160, v212
	v_mov_b32_e32 v161, v213
	v_mov_b32_e32 v162, v214
	v_mov_b32_e32 v163, v215
	v_mov_b32_e32 v170, v216
	v_mov_b32_e32 v171, v217
	v_mov_b32_e32 v172, v218
	v_mov_b32_e32 v173, v219
	v_ashrrev_i32_e32 v159, 31, v158
	v_lshlrev_b64 v[158:159], 11, v[158:159]
	v_lshl_add_u64 v[174:175], s[12:13], 0, v[158:159]
	v_lshl_add_u64 v[174:175], v[174:175], 0, v[146:147]
	s_waitcnt vmcnt(1)
	v_lshlrev_b32_e32 v176, 16, v160
	v_and_b32_e32 v177, 0xffff0000, v160
	v_lshlrev_b32_e32 v160, 16, v161
	v_and_b32_e32 v161, 0xffff0000, v161
	v_lshlrev_b32_e32 v178, 16, v162
	v_and_b32_e32 v179, 0xffff0000, v162
	v_lshlrev_b32_e32 v162, 16, v163
	v_and_b32_e32 v163, 0xffff0000, v163
	s_waitcnt vmcnt(0)
	v_lshlrev_b32_e32 v180, 16, v170
	v_and_b32_e32 v181, 0xffff0000, v170
	v_lshlrev_b32_e32 v170, 16, v171
	v_and_b32_e32 v171, 0xffff0000, v171
	v_lshlrev_b32_e32 v182, 16, v172
	v_and_b32_e32 v183, 0xffff0000, v172
	v_lshlrev_b32_e32 v172, 16, v173
	v_and_b32_e32 v173, 0xffff0000, v173
	v_pk_fma_f32 v[116:117], v[116:117], v[140:141], v[160:161]
	v_pk_fma_f32 v[114:115], v[114:115], v[138:139], v[176:177]
	v_pk_fma_f32 v[108:109], v[108:109], v[144:145], v[162:163]
	v_pk_fma_f32 v[106:107], v[106:107], v[142:143], v[178:179]
	v_pk_fma_f32 v[104:105], v[104:105], v[136:137], v[170:171]
	v_pk_fma_f32 v[102:103], v[102:103], v[134:135], v[180:181]
	v_pk_fma_f32 v[96:97], v[96:97], v[132:133], v[172:173]
	v_pk_fma_f32 v[94:95], v[94:95], v[130:131], v[182:183]
	v_add_u32_e32 v160, 0x90, v164
	v_mov_b32_e32 v170, v220
	v_mov_b32_e32 v171, v221
	v_mov_b32_e32 v172, v222
	v_mov_b32_e32 v173, v223
	s_nop 0
	v_mov_b32_e32 v174, v224
	v_mov_b32_e32 v175, v225
	v_mov_b32_e32 v176, v226
	v_mov_b32_e32 v177, v227
	v_ashrrev_i32_e32 v161, 31, v160
	v_lshlrev_b64 v[160:161], 11, v[160:161]
	v_lshl_add_u64 v[162:163], s[12:13], 0, v[160:161]
	v_lshl_add_u64 v[162:163], v[162:163], 0, v[146:147]
	s_waitcnt vmcnt(1)
	v_lshlrev_b32_e32 v178, 16, v170
	v_and_b32_e32 v179, 0xffff0000, v170
	v_lshlrev_b32_e32 v170, 16, v171
	v_and_b32_e32 v171, 0xffff0000, v171
	v_lshlrev_b32_e32 v180, 16, v172
	v_and_b32_e32 v181, 0xffff0000, v172
	v_lshlrev_b32_e32 v172, 16, v173
	v_and_b32_e32 v173, 0xffff0000, v173
	s_waitcnt vmcnt(0)
	v_lshlrev_b32_e32 v182, 16, v174
	v_and_b32_e32 v183, 0xffff0000, v174
	v_lshlrev_b32_e32 v174, 16, v175
	v_and_b32_e32 v175, 0xffff0000, v175
	v_lshlrev_b32_e32 v184, 16, v176
	v_and_b32_e32 v185, 0xffff0000, v176
	v_lshlrev_b32_e32 v176, 16, v177
	v_and_b32_e32 v177, 0xffff0000, v177
	v_pk_fma_f32 v[128:129], v[128:129], v[140:141], v[170:171]
	v_pk_fma_f32 v[126:127], v[126:127], v[138:139], v[178:179]
	v_pk_fma_f32 v[124:125], v[124:125], v[144:145], v[172:173]
	v_pk_fma_f32 v[122:123], v[122:123], v[142:143], v[180:181]
	v_pk_fma_f32 v[120:121], v[120:121], v[136:137], v[174:175]
	v_pk_fma_f32 v[118:119], v[118:119], v[134:135], v[182:183]
	v_pk_fma_f32 v[112:113], v[112:113], v[132:133], v[176:177]
	v_pk_fma_f32 v[110:111], v[110:111], v[130:131], v[184:185]
	s_nop 0
	v_mov_b32_e32 v170, v228
	v_mov_b32_e32 v171, v229
	v_mov_b32_e32 v172, v230
	v_mov_b32_e32 v173, v231
	v_mov_b32_e32 v174, v232
	v_mov_b32_e32 v175, v233
	v_mov_b32_e32 v176, v234
	v_mov_b32_e32 v177, v235
	v_add_u32_e32 v162, 0xa0, v164
	v_ashrrev_i32_e32 v163, 31, v162
	v_lshlrev_b64 v[162:163], 11, v[162:163]
	v_lshl_add_u64 v[178:179], s[12:13], 0, v[162:163]
	v_lshl_add_u64 v[178:179], v[178:179], 0, v[146:147]
	v_add_u32_e32 v164, 0xb0, v164
	v_ashrrev_i32_e32 v165, 31, v164
	v_lshlrev_b64 v[164:165], 11, v[164:165]
	s_waitcnt vmcnt(1)
	v_lshlrev_b32_e32 v180, 16, v170
	v_and_b32_e32 v181, 0xffff0000, v170
	v_lshlrev_b32_e32 v170, 16, v171
	v_and_b32_e32 v171, 0xffff0000, v171
	v_lshlrev_b32_e32 v182, 16, v172
	v_and_b32_e32 v183, 0xffff0000, v172
	v_lshlrev_b32_e32 v172, 16, v173
	v_and_b32_e32 v173, 0xffff0000, v173
	s_waitcnt vmcnt(0)
	v_lshlrev_b32_e32 v184, 16, v174
	v_and_b32_e32 v185, 0xffff0000, v174
	v_lshlrev_b32_e32 v174, 16, v175
	v_and_b32_e32 v175, 0xffff0000, v175
	v_lshlrev_b32_e32 v186, 16, v176
	v_and_b32_e32 v187, 0xffff0000, v176
	v_lshlrev_b32_e32 v176, 16, v177
	v_and_b32_e32 v177, 0xffff0000, v177
	v_pk_fma_f32 v[88:89], v[88:89], v[140:141], v[170:171]
	v_pk_fma_f32 v[86:87], v[86:87], v[138:139], v[180:181]
	v_pk_fma_f32 v[84:85], v[84:85], v[144:145], v[172:173]
	v_pk_fma_f32 v[82:83], v[82:83], v[142:143], v[182:183]
	v_pk_fma_f32 v[40:41], v[40:41], v[136:137], v[174:175]
	v_pk_fma_f32 v[38:39], v[38:39], v[134:135], v[184:185]
	v_pk_fma_f32 v[36:37], v[36:37], v[132:133], v[176:177]
	v_pk_fma_f32 v[34:35], v[34:35], v[130:131], v[186:187]
	v_mov_b32_e32 v184, v59
	v_mov_b32_e32 v170, v236
	v_mov_b32_e32 v171, v237
	v_mov_b32_e32 v172, v238
	v_mov_b32_e32 v173, v239
	v_mov_b32_e32 v174, v240
	v_mov_b32_e32 v175, v241
	v_mov_b32_e32 v176, v242
	v_mov_b32_e32 v177, v243
	v_lshl_add_u64 v[178:179], s[12:13], 0, v[164:165]
	v_lshl_add_u64 v[180:181], v[178:179], 0, v[146:147]
	v_mov_b32_e32 v185, v60
	v_mov_b32_e32 v186, v58
	v_mov_b32_e32 v187, v61
	v_pk_add_f32 v[184:185], v[184:185], v[186:187]
	s_waitcnt vmcnt(1)
; __device__ __forceinline__ float bf_lo(unsigned w) { return __uint_as_float(w << 16); }
; __device__ __forceinline__ float bf_hi(unsigned w) { return __uint_as_float(w & 0xffff0000u); }
;     template <class Mid> __device__ __forceinline__ bool run(const f32x4 (&v)[2][2][4][2], const Unit& u, int wr, int wc, int fr, int fq, PG8_LAS unsigned char* lds, int wid, int lane, const Mid& mid) const {
;     ...
;         for (int ai = 0; ai < 2; ++ai)
; #pragma unroll
;             for (int m = 0; m < 4; ++m) {
;                 float s = 0.f;
; #pragma unroll
;                 for (int bj = 0; bj < 2; ++bj)
; #pragma unroll
;                     for (int n = 0; n < 2; ++n) { const f32x4 x = v[ai][bj][m][n]; s += (x[0] + x[1]) + (x[2] + x[3]); }
;                 s += __shfl_xor(s, 16); s += __shfl_xor(s, 32);
;                 const float mw = s * (1.0f / 64.0f); float q = 0.f;
; #pragma unroll
;                 for (int bj = 0; bj < 2; ++bj)
; #pragma unroll
;                     for (int n = 0; n < 2; ++n) { const f32x4 d = v[ai][bj][m][n] - mw; q += (d[0] * d[0] + d[1] * d[1]) + (d[2] * d[2] + d[3] * d[3]); }
;                 q += __shfl_xor(q, 16); q += __shfl_xor(q, 32);
;                 if (fq == 0) P[(ai * HALF + wr * 64 + m * 16 + fr) * 4 + wc] = (f32x2v){mw, q};
;     __device__ __forceinline__ void fused(f32x4 (&acc)[2][2][4][2], const Unit& u, int wr, int wc, int fr, int fq, PG8_LAS unsigned char* lds, int wid, int lane) const {
;     ...
;             for (int ai = 0; ai < 2; ++ai)
; #pragma unroll
;                 for (int m = 0; m < 4; ++m) { const int r = ai * HALF + wr * 64 + m * 16 + fr; const size_t off = (size_t)(u.pm * BM + r) * 1024 + col0;
; #pragma unroll
;                     for (int bj = 0; bj < 2; ++bj) { f32x4 b0, b1;
;                         if (XIN_BF16) { const u32x4 w = *(const u32x4*)((const bf16_t*)xin + off + bj * HALF); b0 = (f32x4){bf_lo(w.x), bf_hi(w.x), bf_lo(w.y), bf_hi(w.y)}; b1 = (f32x4){bf_lo(w.z), bf_hi(w.z), bf_lo(w.w), bf_hi(w.w)}; }
;                         else { b0 = *(const f32x4*)((const float*)xin + off + bj * HALF); b1 = *(const f32x4*)((const float*)xin + off + bj * HALF + 4); }
;                         acc[ai][bj][m][0] = b0 + gv[bj][0] * acc[ai][bj][m][0]; acc[ai][bj][m][1] = b1 + gv[bj][1] * acc[ai][bj][m][1]; }
	v_lshlrev_b32_e32 v178, 16, v170
	v_and_b32_e32 v179, 0xffff0000, v170
	v_lshlrev_b32_e32 v170, 16, v171
	v_and_b32_e32 v171, 0xffff0000, v171
	v_lshlrev_b32_e32 v182, 16, v172
	v_and_b32_e32 v183, 0xffff0000, v172
	v_lshlrev_b32_e32 v172, 16, v173
	v_and_b32_e32 v173, 0xffff0000, v173
	s_waitcnt vmcnt(0)
	v_lshlrev_b32_e32 v188, 16, v174
	v_and_b32_e32 v189, 0xffff0000, v174
	v_lshlrev_b32_e32 v174, 16, v175
	v_and_b32_e32 v175, 0xffff0000, v175
	v_lshlrev_b32_e32 v190, 16, v176
	v_and_b32_e32 v191, 0xffff0000, v176
	v_lshlrev_b32_e32 v176, 16, v177
	v_and_b32_e32 v177, 0xffff0000, v177
	v_pk_fma_f32 v[32:33], v[32:33], v[140:141], v[170:171]
	v_pk_fma_f32 v[30:31], v[30:31], v[138:139], v[178:179]
	v_pk_fma_f32 v[28:29], v[28:29], v[144:145], v[172:173]
	v_pk_fma_f32 v[26:27], v[26:27], v[142:143], v[182:183]
	v_pk_fma_f32 v[24:25], v[24:25], v[136:137], v[174:175]
	v_pk_fma_f32 v[22:23], v[22:23], v[134:135], v[188:189]
	v_pk_fma_f32 v[20:21], v[20:21], v[132:133], v[176:177]
	v_pk_fma_f32 v[18:19], v[18:19], v[130:131], v[190:191]
	v_mov_b32_e32 v170, v63
	v_mov_b32_e32 v176, v248
	v_mov_b32_e32 v177, v249
	v_mov_b32_e32 v178, v250
	v_mov_b32_e32 v179, v251
	v_mov_b32_e32 v171, v64
	v_mov_b32_e32 v180, v252
	v_mov_b32_e32 v181, v253
	v_mov_b32_e32 v182, v254
	v_mov_b32_e32 v183, v255
	v_mov_b32_e32 v172, v62
	v_mov_b32_e32 v173, v65
	v_add_f32_e32 v175, v54, v55
	v_add_f32_e32 v189, v56, v57
	v_mov_b32_e32 v174, v46
	v_mov_b32_e32 v188, v47
	v_pk_add_f32 v[170:171], v[170:171], v[172:173]
	v_pk_add_f32 v[172:173], v[174:175], v[188:189]
	v_add_f32_e32 v174, v184, v185
	v_pk_add_f32 v[170:171], v[170:171], v[170:171] op_sel_hi:[0,1]
	v_mov_b32_e32 v190, v49
	v_add_f32_e32 v191, 0, v174
	v_mov_b32_e32 v170, v48
	v_pk_add_f32 v[170:171], v[170:171], v[190:191]
	s_nop 0
	v_pk_add_f32 v[170:171], v[172:173], v[170:171]
	s_nop 0
	v_add_f32_e32 v170, v170, v171
	ds_bpermute_b32 v172, v169, v170
	v_xor_b32_e32 v171, 32, v192
	v_cmp_lt_i32_e32 vcc, v171, v193
	s_waitcnt lgkmcnt(0)
	v_add_f32_e32 v170, v170, v172
	v_cndmask_b32_e32 v171, v192, v171, vcc
	v_lshlrev_b32_e32 v171, 2, v171
	ds_bpermute_b32 v172, v171, v170
	s_waitcnt lgkmcnt(0)
	v_add_f32_e32 v172, v170, v172
	v_fmamk_f32 v173, v172, 0xbc800000, v61
	v_fmamk_f32 v175, v172, 0xbc800000, v59
	v_fmamk_f32 v185, v172, 0xbc800000, v65
	v_fmamk_f32 v187, v172, 0xbc800000, v63
	v_fmamk_f32 v170, v172, 0xbc800000, v60
	v_fmamk_f32 v174, v172, 0xbc800000, v58
	v_fmamk_f32 v184, v172, 0xbc800000, v64
	v_fmamk_f32 v186, v172, 0xbc800000, v62
	v_fmamk_f32 v189, v172, 0xbc800000, v57
	v_fmamk_f32 v191, v172, 0xbc800000, v55
	v_mul_f32_e32 v175, v175, v175
	v_mul_f32_e32 v173, v173, v173
	v_mul_f32_e32 v187, v187, v187
	v_mul_f32_e32 v185, v185, v185
	v_fmamk_f32 v188, v172, 0xbc800000, v56
	v_fmamk_f32 v190, v172, 0xbc800000, v54
	v_fmamk_f32 v193, v172, 0xbc800000, v49
	v_fmamk_f32 v195, v172, 0xbc800000, v47
	v_mul_f32_e32 v191, v191, v191
	v_mul_f32_e32 v189, v189, v189
	v_fmac_f32_e32 v175, v174, v174
	v_fmac_f32_e32 v173, v170, v170
	v_fmac_f32_e32 v187, v186, v186
	v_fmac_f32_e32 v185, v184, v184
	v_fmamk_f32 v192, v172, 0xbc800000, v48
	v_fmamk_f32 v194, v172, 0xbc800000, v46
	v_mul_f32_e32 v195, v195, v195
	v_mul_f32_e32 v193, v193, v193
	v_fmac_f32_e32 v191, v190, v190
	v_fmac_f32_e32 v189, v188, v188
	v_add_f32_e32 v170, v175, v173
	v_add_f32_e32 v173, v187, v185
	v_fmac_f32_e32 v195, v194, v194
	v_fmac_f32_e32 v193, v192, v192
	v_add_f32_e32 v174, v191, v189
	v_add_f32_e32 v170, v170, v173
	v_add_f32_e32 v175, v195, v193
	v_add_f32_e32 v170, v174, v170
	v_add_f32_e32 v173, v175, v170
	ds_bpermute_b32 v174, v169, v173
	v_and_b32_e32 v170, 63, v168
	v_cmp_gt_u32_e32 vcc, 16, v170
	s_waitcnt lgkmcnt(0)
	v_add_f32_e32 v173, v173, v174
	ds_bpermute_b32 v174, v171, v173
	s_waitcnt vmcnt(1)
	v_lshlrev_b32_e32 v184, 16, v176
	v_and_b32_e32 v185, 0xffff0000, v176
	v_lshlrev_b32_e32 v176, 16, v177
	v_and_b32_e32 v177, 0xffff0000, v177
	v_lshlrev_b32_e32 v186, 16, v178
	v_and_b32_e32 v187, 0xffff0000, v178
	v_lshlrev_b32_e32 v178, 16, v179
	v_and_b32_e32 v179, 0xffff0000, v179
	s_waitcnt vmcnt(0)
	v_lshlrev_b32_e32 v188, 16, v180
	v_and_b32_e32 v189, 0xffff0000, v180
	v_lshlrev_b32_e32 v180, 16, v181
	v_and_b32_e32 v181, 0xffff0000, v181
	v_lshlrev_b32_e32 v190, 16, v182
	v_and_b32_e32 v191, 0xffff0000, v182
	v_lshlrev_b32_e32 v182, 16, v183
	v_and_b32_e32 v183, 0xffff0000, v183
	v_pk_fma_f32 v[16:17], v[16:17], v[140:141], v[176:177]
	v_pk_fma_f32 v[14:15], v[14:15], v[138:139], v[184:185]
	v_pk_fma_f32 v[12:13], v[12:13], v[144:145], v[178:179]
	v_pk_fma_f32 v[10:11], v[10:11], v[142:143], v[186:187]
	v_pk_fma_f32 v[8:9], v[8:9], v[136:137], v[180:181]
	v_pk_fma_f32 v[6:7], v[6:7], v[134:135], v[188:189]
	v_pk_fma_f32 v[4:5], v[4:5], v[132:133], v[182:183]
	v_pk_fma_f32 v[2:3], v[2:3], v[130:131], v[190:191]
	s_nop 0
	s_and_saveexec_b64 s[6:7], vcc
	s_cbranch_execz .LBB0_1637
	s_lshl_b32 s9, s24, 11
	s_add_i32 s9, s8, s9
	v_mul_f32_e32 v130, 0x3c800000, v172
	s_waitcnt lgkmcnt(0)
	v_add_f32_e32 v131, v173, v174
	v_lshl_add_u32 v132, v167, 5, s9
	ds_write_b64 v132, v[130:131]

; #define PG8_WAIT_V(n) asm volatile("s_waitcnt vmcnt(" #n ")" ::: "memory")
; #define PG8_BAR __builtin_amdgcn_s_barrier()
; __device__ __forceinline__ float bf_lo(unsigned w) { return __uint_as_float(w << 16); }
; __device__ __forceinline__ float bf_hi(unsigned w) { return __uint_as_float(w & 0xffff0000u); }
; template <class Epi, class Sched, bool ALIGN_EPI = false, bool SP2 = false, bool PAIR_ACC = false>
; __device__ __forceinline__ void gemm_phase(PG8_LAS unsigned char* lds, const Gemm g, const Sched& S, const Epi& E) {
;     ...
;     PG8_WAIT_V(0);
;     if constexpr (!ALIGN_EPI) { if (wr == 0) PG8_BAR; }
;     PG8_BAR;
;     __device__ __forceinline__ void fused(f32x4 (&acc)[2][2][4][2], const Unit& u, int wr, int wc, int fr, int fq, PG8_LAS unsigned char* lds, int wid, int lane) const {
;     ...
;         const int col0 = u.pn * BM + wc * 32 + 8 * fq, b = u.pm >> 4;
;         {
;             f32x4 gv[2][2];
; #pragma unroll
;             for (int bj = 0; bj < 2; ++bj)
; #pragma unroll
;                 for (int n = 0; n < 2; ++n) gv[bj][n] = *(const f32x4*)(g + (size_t)b * 6144 + col0 + bj * HALF + 4 * n);
; #pragma unroll
;             for (int ai = 0; ai < 2; ++ai)
; #pragma unroll
;                 for (int m = 0; m < 4; ++m) { const int r = ai * HALF + wr * 64 + m * 16 + fr; const size_t off = (size_t)(u.pm * BM + r) * 1024 + col0;
; #pragma unroll
;                     for (int bj = 0; bj < 2; ++bj) { f32x4 b0, b1;
;                         if (XIN_BF16) { const u32x4 w = *(const u32x4*)((const bf16_t*)xin + off + bj * HALF); b0 = (f32x4){bf_lo(w.x), bf_hi(w.x), bf_lo(w.y), bf_hi(w.y)}; b1 = (f32x4){bf_lo(w.z), bf_hi(w.z), bf_lo(w.w), bf_hi(w.w)}; }
;                         else { b0 = *(const f32x4*)((const float*)xin + off + bj * HALF); b1 = *(const f32x4*)((const float*)xin + off + bj * HALF + 4); }
;                         acc[ai][bj][m][0] = b0 + gv[bj][0] * acc[ai][bj][m][0]; acc[ai][bj][m][1] = b1 + gv[bj][1] * acc[ai][bj][m][1]; }
.LBB0_1843:
	s_add_u32 s0, s12, 0xc800000
	s_addc_u32 s1, s13, 0
	s_lshl_b32 s2, s34, 5
	s_lshl_b32 s3, s14, 8
	v_lshrrev_b32_e32 v130, 1, v0
	s_or_b32 s2, s3, s2
	v_and_or_b32 v152, v130, 24, s2
	s_ashr_i32 s2, s31, 4
	s_mul_hi_i32 s3, s2, 0x6000
	s_mulk_i32 s2, 0x6000
	s_add_u32 s4, s12, s2
	s_addc_u32 s5, s13, s3
	s_lshl_b32 s2, s31, 8
	v_add_u32_e32 v146, s2, v166
	v_ashrrev_i32_e32 v147, 31, v146
	v_ashrrev_i32_e32 v153, 31, v152
	v_lshlrev_b64 v[130:131], 11, v[146:147]
	v_lshl_add_u64 v[130:131], s[0:1], 0, v[130:131]
	v_lshlrev_b64 v[164:165], 1, v[152:153]
	v_lshl_add_u64 v[130:131], v[130:131], 0, v[164:165]
	v_lshl_add_u64 v[132:133], v[152:153], 2, s[4:5]
	s_mov_b32 s3, 0x1d000
	s_mov_b64 s[98:99], 0x8000
	v_lshl_add_u64 v[244:245], v[130:131], 0, s[98:99]
	global_load_dwordx4 v[192:195], v[244:245], off nt
	global_load_dwordx4 v[196:199], v[244:245], off offset:256 nt
	s_mov_b64 s[98:99], 0x10000
	v_lshl_add_u64 v[244:245], v[130:131], 0, s[98:99]
	global_load_dwordx4 v[200:203], v[244:245], off nt
	global_load_dwordx4 v[204:207], v[244:245], off offset:256 nt
	s_mov_b64 s[98:99], 0x18000
	v_lshl_add_u64 v[244:245], v[130:131], 0, s[98:99]
	global_load_dwordx4 v[208:211], v[244:245], off nt
	global_load_dwordx4 v[212:215], v[244:245], off offset:256 nt
	s_mov_b64 s[98:99], 0x40000
	v_lshl_add_u64 v[244:245], v[130:131], 0, s[98:99]
	global_load_dwordx4 v[216:219], v[244:245], off nt
	global_load_dwordx4 v[220:223], v[244:245], off offset:256 nt
	s_mov_b64 s[98:99], 0x48000
	v_lshl_add_u64 v[244:245], v[130:131], 0, s[98:99]
	global_load_dwordx4 v[224:227], v[244:245], off nt
	global_load_dwordx4 v[228:231], v[244:245], off offset:256 nt
	s_mov_b64 s[98:99], 0x50000
	v_lshl_add_u64 v[244:245], v[130:131], 0, s[98:99]
	global_load_dwordx4 v[232:235], v[244:245], off nt
	global_load_dwordx4 v[236:239], v[244:245], off offset:256 nt
	s_mov_b64 s[98:99], 0x58000
	v_lshl_add_u64 v[244:245], v[130:131], 0, s[98:99]
	global_load_dwordx4 v[240:243], v[244:245], off nt
	global_load_dwordx4 v[248:251], v[244:245], off offset:256 nt
	global_load_dwordx4 v[154:157], v[130:131], off nt
	global_load_dwordx4 v[158:161], v[130:131], off offset:256 nt
	v_add_co_u32_e32 v130, vcc, s3, v132
	s_mov_b64 s[4:5], 0x1d000
	s_nop 0
	v_addc_co_u32_e32 v131, vcc, 0, v133, vcc
	global_load_dwordx4 v[138:141], v[130:131], off nt
	v_lshl_add_u64 v[130:131], v[132:133], 0, s[4:5]
	global_load_dwordx4 v[142:145], v[130:131], off offset:16 nt
	global_load_dwordx4 v[134:137], v[130:131], off offset:512 nt
	s_nop 0
	global_load_dwordx4 v[130:133], v[130:131], off offset:528 nt
	s_waitcnt vmcnt(20)
	s_cmpk_gt_u32 s30, 0xff
	s_cbranch_scc1 .LBB0_1845
	s_barrier
.LBB0_1845:
	s_barrier
	v_add_u32_e32 v148, 16, v146
	v_ashrrev_i32_e32 v149, 31, v148
	v_lshlrev_b64 v[150:151], 11, v[148:149]
	v_lshl_add_u64 v[150:151], s[0:1], 0, v[150:151]
	v_lshl_add_u64 v[150:151], v[150:151], 0, v[164:165]
	v_mbcnt_hi_u32_b32 v188, -1, v1
	v_xor_b32_e32 v1, 16, v188
	s_waitcnt vmcnt(0)
	v_lshlrev_b32_e32 v162, 16, v154
	v_and_b32_e32 v163, 0xffff0000, v154
	v_lshlrev_b32_e32 v154, 16, v155
	v_and_b32_e32 v155, 0xffff0000, v155
	v_lshlrev_b32_e32 v168, 16, v156
	v_and_b32_e32 v169, 0xffff0000, v156
	v_lshlrev_b32_e32 v156, 16, v157
	v_and_b32_e32 v157, 0xffff0000, v157
	v_lshlrev_b32_e32 v170, 16, v158
	v_and_b32_e32 v171, 0xffff0000, v158
	v_lshlrev_b32_e32 v158, 16, v159
	v_and_b32_e32 v159, 0xffff0000, v159
	v_lshlrev_b32_e32 v172, 16, v160
	v_and_b32_e32 v173, 0xffff0000, v160
	v_lshlrev_b32_e32 v160, 16, v161
	v_and_b32_e32 v161, 0xffff0000, v161
	v_pk_fma_f32 v[102:103], v[102:103], v[138:139], v[162:163]
	v_pk_fma_f32 v[104:105], v[104:105], v[140:141], v[154:155]
	v_pk_fma_f32 v[108:109], v[108:109], v[144:145], v[156:157]
	v_pk_fma_f32 v[106:107], v[106:107], v[142:143], v[168:169]
	v_pk_fma_f32 v[88:89], v[88:89], v[136:137], v[158:159]
	v_pk_fma_f32 v[86:87], v[86:87], v[134:135], v[170:171]
	v_pk_fma_f32 v[84:85], v[84:85], v[132:133], v[160:161]
	v_pk_fma_f32 v[82:83], v[82:83], v[130:131], v[172:173]
	s_nop 0
	v_mov_b32_e32 v154, v192
	v_mov_b32_e32 v155, v193
	v_mov_b32_e32 v156, v194
	v_mov_b32_e32 v157, v195
	v_mov_b32_e32 v158, v196
	v_mov_b32_e32 v159, v197
	v_mov_b32_e32 v160, v198
	v_mov_b32_e32 v161, v199
	v_add_u32_e32 v150, 32, v146
	v_ashrrev_i32_e32 v151, 31, v150
	v_lshlrev_b64 v[162:163], 11, v[150:151]
	v_lshl_add_u64 v[162:163], s[0:1], 0, v[162:163]
	v_lshl_add_u64 v[162:163], v[162:163], 0, v[164:165]
	s_waitcnt vmcnt(1)
	v_lshlrev_b32_e32 v168, 16, v154
	v_and_b32_e32 v169, 0xffff0000, v154
	v_lshlrev_b32_e32 v154, 16, v155
	v_and_b32_e32 v155, 0xffff0000, v155
	v_lshlrev_b32_e32 v170, 16, v156
	v_and_b32_e32 v171, 0xffff0000, v156
	v_lshlrev_b32_e32 v156, 16, v157
	v_and_b32_e32 v157, 0xffff0000, v157
	s_waitcnt vmcnt(0)
	v_lshlrev_b32_e32 v172, 16, v158
	v_and_b32_e32 v173, 0xffff0000, v158
	v_lshlrev_b32_e32 v158, 16, v159
	v_and_b32_e32 v159, 0xffff0000, v159
	v_lshlrev_b32_e32 v174, 16, v160
	v_and_b32_e32 v175, 0xffff0000, v160
	v_lshlrev_b32_e32 v160, 16, v161
	v_and_b32_e32 v161, 0xffff0000, v161
	v_pk_fma_f32 v[116:117], v[116:117], v[140:141], v[154:155]
	v_pk_fma_f32 v[114:115], v[114:115], v[138:139], v[168:169]
	v_pk_fma_f32 v[120:121], v[120:121], v[144:145], v[156:157]
	v_pk_fma_f32 v[118:119], v[118:119], v[142:143], v[170:171]
	v_pk_fma_f32 v[96:97], v[96:97], v[136:137], v[158:159]
	v_pk_fma_f32 v[94:95], v[94:95], v[134:135], v[172:173]
	v_pk_fma_f32 v[92:93], v[92:93], v[132:133], v[160:161]
	v_pk_fma_f32 v[90:91], v[90:91], v[130:131], v[174:175]
	v_add_u32_e32 v154, 48, v146
	v_mov_b32_e32 v156, v200
	v_mov_b32_e32 v157, v201
	v_mov_b32_e32 v158, v202
	v_mov_b32_e32 v159, v203
	s_nop 0
	v_mov_b32_e32 v160, v204
	v_mov_b32_e32 v161, v205
	v_mov_b32_e32 v162, v206
	v_mov_b32_e32 v163, v207
	v_ashrrev_i32_e32 v155, 31, v154
	v_lshlrev_b64 v[168:169], 11, v[154:155]
	v_lshl_add_u64 v[168:169], s[0:1], 0, v[168:169]
	v_lshl_add_u64 v[168:169], v[168:169], 0, v[164:165]
	s_waitcnt vmcnt(1)
; __device__ __forceinline__ float bf_lo(unsigned w) { return __uint_as_float(w << 16); }
; __device__ __forceinline__ float bf_hi(unsigned w) { return __uint_as_float(w & 0xffff0000u); }
;     template <class Mid> __device__ __forceinline__ bool run(const f32x4 (&v)[2][2][4][2], const Unit& u, int wr, int wc, int fr, int fq, PG8_LAS unsigned char* lds, int wid, int lane, const Mid& mid) const {
;     ...
;         for (int ai = 0; ai < 2; ++ai)
; #pragma unroll
;             for (int m = 0; m < 4; ++m) {
;                 float s = 0.f;
; #pragma unroll
;                 for (int bj = 0; bj < 2; ++bj)
; #pragma unroll
;                     for (int n = 0; n < 2; ++n) { const f32x4 x = v[ai][bj][m][n]; s += (x[0] + x[1]) + (x[2] + x[3]); }
;     __device__ __forceinline__ void fused(f32x4 (&acc)[2][2][4][2], const Unit& u, int wr, int wc, int fr, int fq, PG8_LAS unsigned char* lds, int wid, int lane) const {
;     ...
;                 for (int m = 0; m < 4; ++m) { const int r = ai * HALF + wr * 64 + m * 16 + fr; const size_t off = (size_t)(u.pm * BM + r) * 1024 + col0;
; #pragma unroll
;                     for (int bj = 0; bj < 2; ++bj) { f32x4 b0, b1;
;                         if (XIN_BF16) { const u32x4 w = *(const u32x4*)((const bf16_t*)xin + off + bj * HALF); b0 = (f32x4){bf_lo(w.x), bf_hi(w.x), bf_lo(w.y), bf_hi(w.y)}; b1 = (f32x4){bf_lo(w.z), bf_hi(w.z), bf_lo(w.w), bf_hi(w.w)}; }
;                         else { b0 = *(const f32x4*)((const float*)xin + off + bj * HALF); b1 = *(const f32x4*)((const float*)xin + off + bj * HALF + 4); }
;                         acc[ai][bj][m][0] = b0 + gv[bj][0] * acc[ai][bj][m][0]; acc[ai][bj][m][1] = b1 + gv[bj][1] * acc[ai][bj][m][1]; }
	v_lshlrev_b32_e32 v170, 16, v156
	v_and_b32_e32 v171, 0xffff0000, v156
	v_lshlrev_b32_e32 v156, 16, v157
	v_and_b32_e32 v157, 0xffff0000, v157
	v_lshlrev_b32_e32 v172, 16, v158
	v_and_b32_e32 v173, 0xffff0000, v158
	v_lshlrev_b32_e32 v158, 16, v159
	v_and_b32_e32 v159, 0xffff0000, v159
	s_waitcnt vmcnt(0)
	v_lshlrev_b32_e32 v174, 16, v160
	v_and_b32_e32 v175, 0xffff0000, v160
	v_lshlrev_b32_e32 v160, 16, v161
	v_and_b32_e32 v161, 0xffff0000, v161
	v_lshlrev_b32_e32 v176, 16, v162
	v_and_b32_e32 v177, 0xffff0000, v162
	v_lshlrev_b32_e32 v162, 16, v163
	v_and_b32_e32 v163, 0xffff0000, v163
	v_pk_fma_f32 v[128:129], v[128:129], v[140:141], v[156:157]
	v_pk_fma_f32 v[126:127], v[126:127], v[138:139], v[170:171]
	v_pk_fma_f32 v[124:125], v[124:125], v[144:145], v[158:159]
	v_pk_fma_f32 v[122:123], v[122:123], v[142:143], v[172:173]
	v_pk_fma_f32 v[112:113], v[112:113], v[136:137], v[160:161]
	v_pk_fma_f32 v[110:111], v[110:111], v[134:135], v[174:175]
	v_pk_fma_f32 v[100:101], v[100:101], v[132:133], v[162:163]
	v_pk_fma_f32 v[98:99], v[98:99], v[130:131], v[176:177]
	v_add_u32_e32 v156, 0x80, v146
	v_mov_b32_e32 v158, v208
	v_mov_b32_e32 v159, v209
	v_mov_b32_e32 v160, v210
	v_mov_b32_e32 v161, v211
	s_nop 0
	v_mov_b32_e32 v168, v212
	v_mov_b32_e32 v169, v213
	v_mov_b32_e32 v170, v214
	v_mov_b32_e32 v171, v215
	v_ashrrev_i32_e32 v157, 31, v156
	v_lshlrev_b64 v[162:163], 11, v[156:157]
	v_lshl_add_u64 v[162:163], s[0:1], 0, v[162:163]
	v_lshl_add_u64 v[172:173], v[162:163], 0, v[164:165]
	s_waitcnt vmcnt(1)
	v_lshlrev_b32_e32 v162, 16, v158
	v_and_b32_e32 v163, 0xffff0000, v158
	v_lshlrev_b32_e32 v158, 16, v159
	v_and_b32_e32 v159, 0xffff0000, v159
	v_lshlrev_b32_e32 v174, 16, v160
	v_and_b32_e32 v175, 0xffff0000, v160
	v_lshlrev_b32_e32 v160, 16, v161
	v_and_b32_e32 v161, 0xffff0000, v161
	s_waitcnt vmcnt(0)
	v_lshlrev_b32_e32 v176, 16, v168
	v_and_b32_e32 v177, 0xffff0000, v168
	v_lshlrev_b32_e32 v168, 16, v169
	v_and_b32_e32 v169, 0xffff0000, v169
	v_lshlrev_b32_e32 v178, 16, v170
	v_and_b32_e32 v179, 0xffff0000, v170
	v_lshlrev_b32_e32 v170, 16, v171
	v_and_b32_e32 v171, 0xffff0000, v171
	v_pk_fma_f32 v[80:81], v[80:81], v[140:141], v[158:159]
	v_pk_fma_f32 v[78:79], v[78:79], v[138:139], v[162:163]
	v_pk_fma_f32 v[76:77], v[76:77], v[144:145], v[160:161]
	v_pk_fma_f32 v[74:75], v[74:75], v[142:143], v[174:175]
	v_pk_fma_f32 v[72:73], v[72:73], v[136:137], v[168:169]
	v_pk_fma_f32 v[70:71], v[70:71], v[134:135], v[176:177]
	v_pk_fma_f32 v[68:69], v[68:69], v[132:133], v[170:171]
	v_pk_fma_f32 v[66:67], v[66:67], v[130:131], v[178:179]
	v_add_u32_e32 v158, 0x90, v146
	v_mov_b32_e32 v160, v216
	v_mov_b32_e32 v161, v217
	v_mov_b32_e32 v162, v218
	v_mov_b32_e32 v163, v219
	v_mov_b32_e32 v168, v220
	v_mov_b32_e32 v169, v221
	v_mov_b32_e32 v170, v222
	v_mov_b32_e32 v171, v223
	v_ashrrev_i32_e32 v159, 31, v158
	v_lshlrev_b64 v[172:173], 11, v[158:159]
	v_lshl_add_u64 v[172:173], s[0:1], 0, v[172:173]
	v_lshl_add_u64 v[172:173], v[172:173], 0, v[164:165]
	s_waitcnt vmcnt(1)
	v_lshlrev_b32_e32 v174, 16, v160
	v_and_b32_e32 v175, 0xffff0000, v160
	v_lshlrev_b32_e32 v160, 16, v161
	v_and_b32_e32 v161, 0xffff0000, v161
	v_lshlrev_b32_e32 v176, 16, v162
	v_and_b32_e32 v177, 0xffff0000, v162
	v_lshlrev_b32_e32 v162, 16, v163
	v_and_b32_e32 v163, 0xffff0000, v163
	s_waitcnt vmcnt(0)
	v_lshlrev_b32_e32 v178, 16, v168
	v_and_b32_e32 v179, 0xffff0000, v168
	v_lshlrev_b32_e32 v168, 16, v169
	v_and_b32_e32 v169, 0xffff0000, v169
	v_lshlrev_b32_e32 v180, 16, v170
	v_and_b32_e32 v181, 0xffff0000, v170
	v_lshlrev_b32_e32 v170, 16, v171
	v_and_b32_e32 v171, 0xffff0000, v171
	v_pk_fma_f32 v[64:65], v[64:65], v[140:141], v[160:161]
	v_pk_fma_f32 v[62:63], v[62:63], v[138:139], v[174:175]
	v_pk_fma_f32 v[60:61], v[60:61], v[144:145], v[162:163]
	v_pk_fma_f32 v[58:59], v[58:59], v[142:143], v[176:177]
	v_pk_fma_f32 v[56:57], v[56:57], v[136:137], v[168:169]
	v_pk_fma_f32 v[54:55], v[54:55], v[134:135], v[178:179]
	v_pk_fma_f32 v[52:53], v[52:53], v[132:133], v[170:171]
	v_pk_fma_f32 v[50:51], v[50:51], v[130:131], v[180:181]
	v_add_u32_e32 v160, 0xa0, v146
	v_mov_b32_e32 v168, v224
	v_mov_b32_e32 v169, v225
	v_mov_b32_e32 v170, v226
	v_mov_b32_e32 v171, v227
	s_nop 0
	v_mov_b32_e32 v172, v228
	v_mov_b32_e32 v173, v229
	v_mov_b32_e32 v174, v230
	v_mov_b32_e32 v175, v231
	v_ashrrev_i32_e32 v161, 31, v160
	v_lshlrev_b64 v[162:163], 11, v[160:161]
	v_lshl_add_u64 v[162:163], s[0:1], 0, v[162:163]
	v_lshl_add_u64 v[162:163], v[162:163], 0, v[164:165]
	s_waitcnt vmcnt(1)
	v_lshlrev_b32_e32 v176, 16, v168
	v_and_b32_e32 v177, 0xffff0000, v168
	v_lshlrev_b32_e32 v168, 16, v169
	v_and_b32_e32 v169, 0xffff0000, v169
	v_lshlrev_b32_e32 v178, 16, v170
	v_and_b32_e32 v179, 0xffff0000, v170
	v_lshlrev_b32_e32 v170, 16, v171
	v_and_b32_e32 v171, 0xffff0000, v171
	s_waitcnt vmcnt(0)
	v_lshlrev_b32_e32 v180, 16, v172
	v_and_b32_e32 v181, 0xffff0000, v172
	v_lshlrev_b32_e32 v172, 16, v173
	v_and_b32_e32 v173, 0xffff0000, v173
	v_lshlrev_b32_e32 v182, 16, v174
	v_and_b32_e32 v183, 0xffff0000, v174
	v_lshlrev_b32_e32 v174, 16, v175
	v_and_b32_e32 v175, 0xffff0000, v175
	v_pk_fma_f32 v[48:49], v[48:49], v[140:141], v[168:169]
	v_pk_fma_f32 v[46:47], v[46:47], v[138:139], v[176:177]
	v_pk_fma_f32 v[44:45], v[44:45], v[144:145], v[170:171]
	v_pk_fma_f32 v[42:43], v[42:43], v[142:143], v[178:179]
	v_pk_fma_f32 v[40:41], v[40:41], v[136:137], v[172:173]
	v_pk_fma_f32 v[38:39], v[38:39], v[134:135], v[180:181]
	v_pk_fma_f32 v[36:37], v[36:37], v[132:133], v[174:175]
	v_pk_fma_f32 v[34:35], v[34:35], v[130:131], v[182:183]
	v_mov_b32_e32 v180, v103
	v_mov_b32_e32 v168, v232
	v_mov_b32_e32 v169, v233
	v_mov_b32_e32 v170, v234
	v_mov_b32_e32 v171, v235
	v_mov_b32_e32 v172, v236
	v_mov_b32_e32 v173, v237
	v_mov_b32_e32 v174, v238
	v_mov_b32_e32 v175, v239
	v_and_b32_e32 v162, 64, v188
	v_add_u32_e32 v189, 64, v162
	v_add_u32_e32 v162, 0xb0, v146
	v_ashrrev_i32_e32 v163, 31, v162
	v_lshlrev_b64 v[176:177], 11, v[162:163]
	v_lshl_add_u64 v[176:177], s[0:1], 0, v[176:177]
	v_lshl_add_u64 v[164:165], v[176:177], 0, v[164:165]
	v_mov_b32_e32 v181, v104
	v_mov_b32_e32 v182, v102
	v_mov_b32_e32 v183, v105
	v_pk_add_f32 v[180:181], v[180:181], v[182:183]
	v_cmp_lt_i32_e32 vcc, v1, v189
	s_lshl_b32 s0, s34, 3
	s_add_i32 s3, s0, 0
	v_cndmask_b32_e32 v1, v188, v1, vcc
	v_lshlrev_b32_e32 v1, 2, v1
	s_waitcnt vmcnt(1)
; __device__ __forceinline__ float bf_lo(unsigned w) { return __uint_as_float(w << 16); }
; __device__ __forceinline__ float bf_hi(unsigned w) { return __uint_as_float(w & 0xffff0000u); }
;     template <class Mid> __device__ __forceinline__ bool run(const f32x4 (&v)[2][2][4][2], const Unit& u, int wr, int wc, int fr, int fq, PG8_LAS unsigned char* lds, int wid, int lane, const Mid& mid) const {
;     ...
;                 for (int bj = 0; bj < 2; ++bj)
; #pragma unroll
;                     for (int n = 0; n < 2; ++n) { const f32x4 x = v[ai][bj][m][n]; s += (x[0] + x[1]) + (x[2] + x[3]); }
;                 s += __shfl_xor(s, 16); s += __shfl_xor(s, 32);
;                 const float mw = s * (1.0f / 64.0f); float q = 0.f;
; #pragma unroll
;                 for (int bj = 0; bj < 2; ++bj)
; #pragma unroll
;                     for (int n = 0; n < 2; ++n) { const f32x4 d = v[ai][bj][m][n] - mw; q += (d[0] * d[0] + d[1] * d[1]) + (d[2] * d[2] + d[3] * d[3]); }
;                 q += __shfl_xor(q, 16); q += __shfl_xor(q, 32);
;                 if (fq == 0) P[(ai * HALF + wr * 64 + m * 16 + fr) * 4 + wc] = (f32x2v){mw, q};
;     __device__ __forceinline__ void fused(f32x4 (&acc)[2][2][4][2], const Unit& u, int wr, int wc, int fr, int fq, PG8_LAS unsigned char* lds, int wid, int lane) const {
;     ...
;                     for (int bj = 0; bj < 2; ++bj) { f32x4 b0, b1;
;                         if (XIN_BF16) { const u32x4 w = *(const u32x4*)((const bf16_t*)xin + off + bj * HALF); b0 = (f32x4){bf_lo(w.x), bf_hi(w.x), bf_lo(w.y), bf_hi(w.y)}; b1 = (f32x4){bf_lo(w.z), bf_hi(w.z), bf_lo(w.w), bf_hi(w.w)}; }
;                         else { b0 = *(const f32x4*)((const float*)xin + off + bj * HALF); b1 = *(const f32x4*)((const float*)xin + off + bj * HALF + 4); }
;                         acc[ai][bj][m][0] = b0 + gv[bj][0] * acc[ai][bj][m][0]; acc[ai][bj][m][1] = b1 + gv[bj][1] * acc[ai][bj][m][1]; }
	v_lshlrev_b32_e32 v176, 16, v168
	v_and_b32_e32 v177, 0xffff0000, v168
	v_lshlrev_b32_e32 v168, 16, v169
	v_and_b32_e32 v169, 0xffff0000, v169
	v_lshlrev_b32_e32 v178, 16, v170
	v_and_b32_e32 v179, 0xffff0000, v170
	v_lshlrev_b32_e32 v170, 16, v171
	v_and_b32_e32 v171, 0xffff0000, v171
	s_waitcnt vmcnt(0)
	v_lshlrev_b32_e32 v184, 16, v172
	v_and_b32_e32 v185, 0xffff0000, v172
	v_lshlrev_b32_e32 v172, 16, v173
	v_and_b32_e32 v173, 0xffff0000, v173
	v_lshlrev_b32_e32 v186, 16, v174
	v_and_b32_e32 v187, 0xffff0000, v174
	v_lshlrev_b32_e32 v174, 16, v175
	v_and_b32_e32 v175, 0xffff0000, v175
	v_pk_fma_f32 v[32:33], v[32:33], v[140:141], v[168:169]
	v_pk_fma_f32 v[30:31], v[30:31], v[138:139], v[176:177]
	v_pk_fma_f32 v[28:29], v[28:29], v[144:145], v[170:171]
	v_pk_fma_f32 v[26:27], v[26:27], v[142:143], v[178:179]
	v_pk_fma_f32 v[24:25], v[24:25], v[136:137], v[172:173]
	v_pk_fma_f32 v[22:23], v[22:23], v[134:135], v[184:185]
	v_pk_fma_f32 v[20:21], v[20:21], v[132:133], v[174:175]
	v_pk_fma_f32 v[18:19], v[18:19], v[130:131], v[186:187]
	v_mov_b32_e32 v168, v107
	v_mov_b32_e32 v172, v240
	v_mov_b32_e32 v173, v241
	v_mov_b32_e32 v174, v242
	v_mov_b32_e32 v175, v243
	v_mov_b32_e32 v176, v248
	v_mov_b32_e32 v177, v249
	v_mov_b32_e32 v178, v250
	v_mov_b32_e32 v179, v251
	v_mov_b32_e32 v169, v108
	v_mov_b32_e32 v170, v106
	v_mov_b32_e32 v171, v109
	v_pk_add_f32 v[168:169], v[168:169], v[170:171]
	v_add_f32_e32 v165, v180, v181
	v_pk_add_f32 v[168:169], v[168:169], v[168:169] op_sel_hi:[0,1]
	v_add_f32_e32 v185, v86, v87
	v_add_f32_e32 v187, v88, v89
	v_mov_b32_e32 v184, v82
	v_mov_b32_e32 v186, v83
	v_mov_b32_e32 v164, v85
	v_add_f32_e32 v165, 0, v165
	v_mov_b32_e32 v168, v84
	v_pk_add_f32 v[170:171], v[184:185], v[186:187]
	v_pk_add_f32 v[164:165], v[168:169], v[164:165]
	s_nop 0
	v_pk_add_f32 v[164:165], v[170:171], v[164:165]
	s_nop 0
	v_add_f32_e32 v164, v164, v165
	ds_bpermute_b32 v168, v1, v164
	v_xor_b32_e32 v165, 32, v188
	v_cmp_lt_i32_e32 vcc, v165, v189
	s_waitcnt lgkmcnt(0)
	v_add_f32_e32 v164, v164, v168
	v_cndmask_b32_e32 v165, v188, v165, vcc
	v_lshlrev_b32_e32 v165, 2, v165
	ds_bpermute_b32 v168, v165, v164
	s_waitcnt lgkmcnt(0)
	v_add_f32_e32 v168, v164, v168
	v_fmamk_f32 v169, v168, 0xbc800000, v105
	v_fmamk_f32 v171, v168, 0xbc800000, v103
	v_fmamk_f32 v181, v168, 0xbc800000, v109
	v_fmamk_f32 v183, v168, 0xbc800000, v107
	v_fmamk_f32 v164, v168, 0xbc800000, v104
	v_fmamk_f32 v170, v168, 0xbc800000, v102
	v_fmamk_f32 v180, v168, 0xbc800000, v108
	v_fmamk_f32 v182, v168, 0xbc800000, v106
	v_fmamk_f32 v185, v168, 0xbc800000, v89
	v_fmamk_f32 v187, v168, 0xbc800000, v87
	v_mul_f32_e32 v171, v171, v171
	v_mul_f32_e32 v169, v169, v169
	v_mul_f32_e32 v183, v183, v183
	v_mul_f32_e32 v181, v181, v181
	v_fmamk_f32 v184, v168, 0xbc800000, v88
	v_fmamk_f32 v186, v168, 0xbc800000, v86
	v_fmamk_f32 v189, v168, 0xbc800000, v85
	v_fmamk_f32 v191, v168, 0xbc800000, v83
	v_mul_f32_e32 v187, v187, v187
	v_mul_f32_e32 v185, v185, v185
	v_fmac_f32_e32 v171, v170, v170
	v_fmac_f32_e32 v169, v164, v164
	v_fmac_f32_e32 v183, v182, v182
	v_fmac_f32_e32 v181, v180, v180
	v_fmamk_f32 v188, v168, 0xbc800000, v84
	v_fmamk_f32 v190, v168, 0xbc800000, v82
	v_mul_f32_e32 v191, v191, v191
	v_mul_f32_e32 v189, v189, v189
	v_fmac_f32_e32 v187, v186, v186
	v_fmac_f32_e32 v185, v184, v184
	v_add_f32_e32 v164, v171, v169
	v_add_f32_e32 v169, v183, v181
	v_fmac_f32_e32 v191, v190, v190
	v_fmac_f32_e32 v189, v188, v188
	v_add_f32_e32 v170, v187, v185
	v_add_f32_e32 v164, v164, v169
	v_add_f32_e32 v171, v191, v189
	v_add_f32_e32 v164, v170, v164
	v_add_f32_e32 v169, v171, v164
	ds_bpermute_b32 v170, v1, v169
	v_and_b32_e32 v164, 63, v0
	v_cmp_gt_u32_e32 vcc, 16, v164
	s_waitcnt lgkmcnt(0)
	v_add_f32_e32 v169, v169, v170
	ds_bpermute_b32 v170, v165, v169
	s_waitcnt vmcnt(1)
	v_lshlrev_b32_e32 v180, 16, v172
	v_and_b32_e32 v181, 0xffff0000, v172
	v_lshlrev_b32_e32 v172, 16, v173
	v_and_b32_e32 v173, 0xffff0000, v173
	v_lshlrev_b32_e32 v182, 16, v174
	v_and_b32_e32 v183, 0xffff0000, v174
	v_lshlrev_b32_e32 v174, 16, v175
	v_and_b32_e32 v175, 0xffff0000, v175
	s_waitcnt vmcnt(0)
	v_lshlrev_b32_e32 v184, 16, v176
	v_and_b32_e32 v185, 0xffff0000, v176
	v_lshlrev_b32_e32 v176, 16, v177
	v_and_b32_e32 v177, 0xffff0000, v177
	v_lshlrev_b32_e32 v186, 16, v178
	v_and_b32_e32 v187, 0xffff0000, v178
	v_lshlrev_b32_e32 v178, 16, v179
	v_and_b32_e32 v179, 0xffff0000, v179
	v_pk_fma_f32 v[16:17], v[16:17], v[140:141], v[172:173]
	v_pk_fma_f32 v[14:15], v[14:15], v[138:139], v[180:181]
	v_pk_fma_f32 v[12:13], v[12:13], v[144:145], v[174:175]
	v_pk_fma_f32 v[10:11], v[10:11], v[142:143], v[182:183]
	v_pk_fma_f32 v[8:9], v[8:9], v[136:137], v[176:177]
	v_pk_fma_f32 v[6:7], v[6:7], v[134:135], v[184:185]
	v_pk_fma_f32 v[4:5], v[4:5], v[132:133], v[178:179]
	v_pk_fma_f32 v[2:3], v[2:3], v[130:131], v[186:187]
	s_nop 0
	s_and_saveexec_b64 s[0:1], vcc
	s_cbranch_execz .LBB0_1847
	s_lshl_b32 s4, s33, 11
	s_add_i32 s4, s3, s4
	v_mul_f32_e32 v130, 0x3c800000, v168
	s_waitcnt lgkmcnt(0)
	v_add_f32_e32 v131, v169, v170
	v_lshl_add_u32 v132, v167, 5, s4
	ds_write_b64 v132, v[130:131]
